# GEMM K-loop LDS-DMA loads with uniform base use the saddr form (no per-load 64-bit VALU address add)
# baseline (speedup 1.0000x reference)
.LBB0_67:
	s_add_u32 s34, s6, 0xfff80080
	s_addc_u32 s35, s7, -1
	s_add_i32 s53, 0, 0x10000
	s_cmp_eq_u32 s52, 28
	s_cselect_b32 s37, s25, s35
	s_cselect_b32 s36, s29, s34
	s_cselect_b32 s35, s23, s51
	s_cselect_b32 s34, s49, s50
	s_add_i32 s56, 0, 0x14000
	v_add_u32_e32 v142, s53, v187
	v_add_u32_e32 v158, s56, v187
	ds_read_b128 v[130:133], v142
	ds_read_b128 v[134:137], v142 offset:1024
	ds_read_b128 v[138:141], v142 offset:2048
	ds_read_b128 v[142:145], v142 offset:3072
	ds_read_b128 v[146:149], v158
	ds_read_b128 v[150:153], v158 offset:1024
	ds_read_b128 v[154:157], v158 offset:2048
	ds_read_b128 v[158:161], v158 offset:3072
	s_add_i32 m0, s43, 0xc000
	ds_read_b128 v[172:175], v199
	ds_read_b128 v[178:181], v199 offset:1024
	ds_read_b128 v[188:191], v199 offset:2048
	ds_read_b128 v[200:203], v199 offset:3072
	ds_read_b128 v[204:207], v199 offset:4096
	ds_read_b128 v[216:219], v199 offset:5120
	ds_read_b128 v[220:223], v199 offset:6144
	ds_read_b128 v[224:227], v199 offset:7168
	global_load_lds_dwordx4 v168, s[6:7]
	s_add_i32 m0, s43, 0xe000
	s_nop 0
	global_load_lds_dwordx4 v170, s[6:7]
	s_waitcnt vmcnt(8) lgkmcnt(0)
	s_barrier
	s_setprio 1
	v_mfma_f32_16x16x32_bf16 v[126:129], v[130:133], v[172:175], v[126:129]
	v_mfma_f32_16x16x32_bf16 v[122:125], v[138:141], v[172:175], v[122:125]
	v_mfma_f32_16x16x32_bf16 v[110:113], v[130:133], v[188:191], v[110:113]
	v_mfma_f32_16x16x32_bf16 v[106:109], v[138:141], v[188:191], v[106:109]
	v_mfma_f32_16x16x32_bf16 v[98:101], v[130:133], v[204:207], v[98:101]
	v_mfma_f32_16x16x32_bf16 v[90:93], v[138:141], v[204:207], v[90:93]
	v_mfma_f32_16x16x32_bf16 v[82:85], v[130:133], v[220:223], v[82:85]
	v_mfma_f32_16x16x32_bf16 v[74:77], v[138:141], v[220:223], v[74:77]
	v_mfma_f32_16x16x32_bf16 v[126:129], v[134:137], v[178:181], v[126:129]
	v_mfma_f32_16x16x32_bf16 v[122:125], v[142:145], v[178:181], v[122:125]
	v_mfma_f32_16x16x32_bf16 v[110:113], v[134:137], v[200:203], v[110:113]
	v_mfma_f32_16x16x32_bf16 v[106:109], v[142:145], v[200:203], v[106:109]
	v_mfma_f32_16x16x32_bf16 v[98:101], v[134:137], v[216:219], v[98:101]
	v_mfma_f32_16x16x32_bf16 v[90:93], v[142:145], v[216:219], v[90:93]
	v_mfma_f32_16x16x32_bf16 v[82:85], v[134:137], v[224:227], v[82:85]
	v_mfma_f32_16x16x32_bf16 v[74:77], v[142:145], v[224:227], v[74:77]
	v_mfma_f32_16x16x32_bf16 v[118:121], v[146:149], v[172:175], v[118:121]
	v_mfma_f32_16x16x32_bf16 v[114:117], v[154:157], v[172:175], v[114:117]
	v_mfma_f32_16x16x32_bf16 v[102:105], v[146:149], v[188:191], v[102:105]
	v_mfma_f32_16x16x32_bf16 v[94:97], v[154:157], v[188:191], v[94:97]
	v_mfma_f32_16x16x32_bf16 v[86:89], v[146:149], v[204:207], v[86:89]
	v_mfma_f32_16x16x32_bf16 v[78:81], v[154:157], v[204:207], v[78:81]
	v_mfma_f32_16x16x32_bf16 v[70:73], v[146:149], v[220:223], v[70:73]
	v_mfma_f32_16x16x32_bf16 v[66:69], v[154:157], v[220:223], v[66:69]
	v_mfma_f32_16x16x32_bf16 v[118:121], v[150:153], v[178:181], v[118:121]
	v_mfma_f32_16x16x32_bf16 v[114:117], v[158:161], v[178:181], v[114:117]
	v_mfma_f32_16x16x32_bf16 v[102:105], v[150:153], v[200:203], v[102:105]
	v_mfma_f32_16x16x32_bf16 v[94:97], v[158:161], v[200:203], v[94:97]
	v_mfma_f32_16x16x32_bf16 v[86:89], v[150:153], v[216:219], v[86:89]
	v_mfma_f32_16x16x32_bf16 v[78:81], v[158:161], v[216:219], v[78:81]
	v_mfma_f32_16x16x32_bf16 v[70:73], v[150:153], v[224:227], v[70:73]
	v_mfma_f32_16x16x32_bf16 v[66:69], v[158:161], v[224:227], v[66:69]
	s_setprio 0
	s_barrier
	s_add_i32 s53, s53, s42
	v_lshl_add_u64 v[184:185], s[34:35], 0, v[210:211]
	s_mov_b32 m0, s53
	ds_read_b128 v[172:175], v199 offset:16384
	ds_read_b128 v[178:181], v199 offset:17408
	ds_read_b128 v[188:191], v199 offset:18432
	ds_read_b128 v[200:203], v199 offset:19456
	ds_read_b128 v[204:207], v199 offset:20480
	ds_read_b128 v[216:219], v199 offset:21504
	ds_read_b128 v[220:223], v199 offset:22528
	ds_read_b128 v[224:227], v199 offset:23552
	global_load_lds_dwordx4 v[184:185], off
	s_add_i32 m0, s53, 0x2000
	s_add_u32 s54, s34, 0x80000
	v_lshl_add_u64 v[192:193], s[34:35], 0, v[162:163]
	s_addc_u32 s55, s35, 0
	s_add_i32 s53, s56, s42
	global_load_lds_dwordx4 v[192:193], off
	s_mov_b32 m0, s53
	v_lshl_add_u64 v[208:209], s[36:37], 0, v[164:165]
	global_load_lds_dwordx4 v210, s[54:55]
	s_add_i32 m0, s53, 0x2000
	s_nop 0
	global_load_lds_dwordx4 v162, s[54:55]
	v_lshl_add_u64 v[196:197], s[36:37], 0, v[166:167]
	s_mov_b32 m0, s43
	s_nop 0
	global_load_lds_dwordx4 v[196:197], off
	s_mov_b32 m0, s44
	s_nop 0
	global_load_lds_dwordx4 v[208:209], off
	s_waitcnt vmcnt(8) lgkmcnt(0)
	s_barrier
	s_setprio 1
	v_mfma_f32_16x16x32_bf16 v[62:65], v[130:133], v[172:175], v[62:65]
	v_mfma_f32_16x16x32_bf16 v[58:61], v[138:141], v[172:175], v[58:61]
	v_mfma_f32_16x16x32_bf16 v[50:53], v[130:133], v[188:191], v[50:53]
	v_mfma_f32_16x16x32_bf16 v[42:45], v[138:141], v[188:191], v[42:45]
	v_mfma_f32_16x16x32_bf16 v[34:37], v[130:133], v[204:207], v[34:37]
	v_mfma_f32_16x16x32_bf16 v[26:29], v[138:141], v[204:207], v[26:29]
	v_mfma_f32_16x16x32_bf16 v[14:17], v[130:133], v[220:223], v[14:17]
	v_mfma_f32_16x16x32_bf16 v[10:13], v[138:141], v[220:223], v[10:13]
	v_mfma_f32_16x16x32_bf16 v[62:65], v[134:137], v[178:181], v[62:65]
	v_mfma_f32_16x16x32_bf16 v[58:61], v[142:145], v[178:181], v[58:61]
	v_mfma_f32_16x16x32_bf16 v[50:53], v[134:137], v[200:203], v[50:53]
	v_mfma_f32_16x16x32_bf16 v[42:45], v[142:145], v[200:203], v[42:45]
	v_mfma_f32_16x16x32_bf16 v[34:37], v[134:137], v[216:219], v[34:37]
	v_mfma_f32_16x16x32_bf16 v[26:29], v[142:145], v[216:219], v[26:29]
	v_mfma_f32_16x16x32_bf16 v[14:17], v[134:137], v[224:227], v[14:17]
	v_mfma_f32_16x16x32_bf16 v[10:13], v[142:145], v[224:227], v[10:13]
	v_mfma_f32_16x16x32_bf16 v[54:57], v[146:149], v[172:175], v[54:57]
	v_mfma_f32_16x16x32_bf16 v[46:49], v[154:157], v[172:175], v[46:49]
	v_mfma_f32_16x16x32_bf16 v[38:41], v[146:149], v[188:191], v[38:41]
	v_mfma_f32_16x16x32_bf16 v[30:33], v[154:157], v[188:191], v[30:33]
	v_mfma_f32_16x16x32_bf16 v[22:25], v[146:149], v[204:207], v[22:25]
	v_mfma_f32_16x16x32_bf16 v[18:21], v[154:157], v[204:207], v[18:21]
	v_mfma_f32_16x16x32_bf16 v[6:9], v[146:149], v[220:223], v[6:9]
	v_mfma_f32_16x16x32_bf16 v[2:5], v[154:157], v[220:223], v[2:5]
	v_mfma_f32_16x16x32_bf16 v[54:57], v[150:153], v[178:181], v[54:57]
	v_mfma_f32_16x16x32_bf16 v[46:49], v[158:161], v[178:181], v[46:49]
	v_mfma_f32_16x16x32_bf16 v[38:41], v[150:153], v[200:203], v[38:41]
	v_mfma_f32_16x16x32_bf16 v[30:33], v[158:161], v[200:203], v[30:33]
	v_mfma_f32_16x16x32_bf16 v[22:25], v[150:153], v[216:219], v[22:25]
	v_mfma_f32_16x16x32_bf16 v[18:21], v[158:161], v[216:219], v[18:21]
	v_mfma_f32_16x16x32_bf16 v[6:9], v[150:153], v[224:227], v[6:9]
	v_mfma_f32_16x16x32_bf16 v[2:5], v[158:161], v[224:227], v[2:5]
	s_setprio 0
	s_barrier
	s_add_i32 s53, 0, 0x18000
	s_add_i32 s54, 0, 0x1c000
	v_add_u32_e32 v142, s53, v187
	v_add_u32_e32 v158, s54, v187
	ds_read_b128 v[130:133], v142
	ds_read_b128 v[134:137], v142 offset:1024
	ds_read_b128 v[138:141], v142 offset:2048
	ds_read_b128 v[142:145], v142 offset:3072
	ds_read_b128 v[146:149], v158
	ds_read_b128 v[150:153], v158 offset:1024
	ds_read_b128 v[154:157], v158 offset:2048
	ds_read_b128 v[158:161], v158 offset:3072
	s_add_u32 s36, s36, 0x80000
	s_addc_u32 s37, s37, 0
	s_mov_b32 m0, s45
	ds_read_b128 v[172:175], v199 offset:32768
	ds_read_b128 v[178:181], v199 offset:33792
	ds_read_b128 v[188:191], v199 offset:34816
	ds_read_b128 v[200:203], v199 offset:35840
	ds_read_b128 v[204:207], v199 offset:36864
	ds_read_b128 v[216:219], v199 offset:37888
	ds_read_b128 v[220:223], v199 offset:38912
	ds_read_b128 v[224:227], v199 offset:39936
	global_load_lds_dwordx4 v166, s[36:37]
	s_mov_b32 m0, s46
	s_nop 0
	global_load_lds_dwordx4 v164, s[36:37]
	s_waitcnt vmcnt(8) lgkmcnt(0)
	s_barrier
	s_setprio 1
	v_mfma_f32_16x16x32_bf16 v[126:129], v[130:133], v[172:175], v[126:129]
	v_mfma_f32_16x16x32_bf16 v[122:125], v[138:141], v[172:175], v[122:125]
	v_mfma_f32_16x16x32_bf16 v[110:113], v[130:133], v[188:191], v[110:113]
	v_mfma_f32_16x16x32_bf16 v[106:109], v[138:141], v[188:191], v[106:109]
	v_mfma_f32_16x16x32_bf16 v[98:101], v[130:133], v[204:207], v[98:101]
	v_mfma_f32_16x16x32_bf16 v[90:93], v[138:141], v[204:207], v[90:93]
	v_mfma_f32_16x16x32_bf16 v[82:85], v[130:133], v[220:223], v[82:85]
	v_mfma_f32_16x16x32_bf16 v[74:77], v[138:141], v[220:223], v[74:77]
	v_mfma_f32_16x16x32_bf16 v[126:129], v[134:137], v[178:181], v[126:129]
	v_mfma_f32_16x16x32_bf16 v[122:125], v[142:145], v[178:181], v[122:125]
	v_mfma_f32_16x16x32_bf16 v[110:113], v[134:137], v[200:203], v[110:113]
	v_mfma_f32_16x16x32_bf16 v[106:109], v[142:145], v[200:203], v[106:109]
	v_mfma_f32_16x16x32_bf16 v[98:101], v[134:137], v[216:219], v[98:101]
	v_mfma_f32_16x16x32_bf16 v[90:93], v[142:145], v[216:219], v[90:93]
	v_mfma_f32_16x16x32_bf16 v[82:85], v[134:137], v[224:227], v[82:85]
	v_mfma_f32_16x16x32_bf16 v[74:77], v[142:145], v[224:227], v[74:77]
	v_mfma_f32_16x16x32_bf16 v[118:121], v[146:149], v[172:175], v[118:121]
	v_mfma_f32_16x16x32_bf16 v[114:117], v[154:157], v[172:175], v[114:117]
	v_mfma_f32_16x16x32_bf16 v[102:105], v[146:149], v[188:191], v[102:105]
	v_mfma_f32_16x16x32_bf16 v[94:97], v[154:157], v[188:191], v[94:97]
	v_mfma_f32_16x16x32_bf16 v[86:89], v[146:149], v[204:207], v[86:89]
	v_mfma_f32_16x16x32_bf16 v[78:81], v[154:157], v[204:207], v[78:81]
	v_mfma_f32_16x16x32_bf16 v[70:73], v[146:149], v[220:223], v[70:73]
	v_mfma_f32_16x16x32_bf16 v[66:69], v[154:157], v[220:223], v[66:69]
	v_mfma_f32_16x16x32_bf16 v[118:121], v[150:153], v[178:181], v[118:121]
	v_mfma_f32_16x16x32_bf16 v[114:117], v[158:161], v[178:181], v[114:117]
	v_mfma_f32_16x16x32_bf16 v[102:105], v[150:153], v[200:203], v[102:105]
	v_mfma_f32_16x16x32_bf16 v[94:97], v[158:161], v[200:203], v[94:97]
	v_mfma_f32_16x16x32_bf16 v[86:89], v[150:153], v[216:219], v[86:89]
	v_mfma_f32_16x16x32_bf16 v[78:81], v[158:161], v[216:219], v[78:81]
	v_mfma_f32_16x16x32_bf16 v[70:73], v[150:153], v[224:227], v[70:73]
	v_mfma_f32_16x16x32_bf16 v[66:69], v[158:161], v[224:227], v[66:69]
	s_setprio 0
	s_barrier
	s_add_i32 s36, s53, s42
	v_lshl_add_u64 v[184:185], v[184:185], 0, s[64:65]
	s_mov_b32 m0, s36
	ds_read_b128 v[172:175], v199 offset:49152
	ds_read_b128 v[178:181], v199 offset:50176
	ds_read_b128 v[188:191], v199 offset:51200
	ds_read_b128 v[200:203], v199 offset:52224
	ds_read_b128 v[204:207], v199 offset:53248
	ds_read_b128 v[216:219], v199 offset:54272
	ds_read_b128 v[220:223], v199 offset:55296
	ds_read_b128 v[224:227], v199 offset:56320
	global_load_lds_dwordx4 v[184:185], off
	s_add_i32 m0, s36, 0x2000
	s_add_u32 s34, s34, 0x80080
	v_lshl_add_u64 v[184:185], v[192:193], 0, s[64:65]
	s_addc_u32 s35, s35, 0
	s_add_i32 s36, s54, s42
	global_load_lds_dwordx4 v[184:185], off
	s_mov_b32 m0, s36
	s_nop 0
	global_load_lds_dwordx4 v210, s[34:35]
	s_add_i32 m0, s36, 0x2000
	s_nop 0
	global_load_lds_dwordx4 v162, s[34:35]
	v_lshl_add_u64 v[184:185], v[196:197], 0, s[64:65]
	s_mov_b32 m0, s47
	s_nop 0
	global_load_lds_dwordx4 v[184:185], off
	v_lshl_add_u64 v[184:185], v[208:209], 0, s[64:65]
	s_mov_b32 m0, s48
	s_nop 0
	global_load_lds_dwordx4 v[184:185], off
	s_waitcnt vmcnt(8) lgkmcnt(0)
	s_barrier
	s_setprio 1
	v_mfma_f32_16x16x32_bf16 v[62:65], v[130:133], v[172:175], v[62:65]
	v_mfma_f32_16x16x32_bf16 v[58:61], v[138:141], v[172:175], v[58:61]
	v_mfma_f32_16x16x32_bf16 v[50:53], v[130:133], v[188:191], v[50:53]
	v_mfma_f32_16x16x32_bf16 v[42:45], v[138:141], v[188:191], v[42:45]
	v_mfma_f32_16x16x32_bf16 v[34:37], v[130:133], v[204:207], v[34:37]
	v_mfma_f32_16x16x32_bf16 v[26:29], v[138:141], v[204:207], v[26:29]
	v_mfma_f32_16x16x32_bf16 v[14:17], v[130:133], v[220:223], v[14:17]
	v_mfma_f32_16x16x32_bf16 v[10:13], v[138:141], v[220:223], v[10:13]
	v_mfma_f32_16x16x32_bf16 v[62:65], v[134:137], v[178:181], v[62:65]
	v_mfma_f32_16x16x32_bf16 v[58:61], v[142:145], v[178:181], v[58:61]
	v_mfma_f32_16x16x32_bf16 v[50:53], v[134:137], v[200:203], v[50:53]
	v_mfma_f32_16x16x32_bf16 v[42:45], v[142:145], v[200:203], v[42:45]
	v_mfma_f32_16x16x32_bf16 v[34:37], v[134:137], v[216:219], v[34:37]
	v_mfma_f32_16x16x32_bf16 v[26:29], v[142:145], v[216:219], v[26:29]
	v_mfma_f32_16x16x32_bf16 v[14:17], v[134:137], v[224:227], v[14:17]
	v_mfma_f32_16x16x32_bf16 v[10:13], v[142:145], v[224:227], v[10:13]
	v_mfma_f32_16x16x32_bf16 v[54:57], v[146:149], v[172:175], v[54:57]
	v_mfma_f32_16x16x32_bf16 v[46:49], v[154:157], v[172:175], v[46:49]
	v_mfma_f32_16x16x32_bf16 v[38:41], v[146:149], v[188:191], v[38:41]
	v_mfma_f32_16x16x32_bf16 v[30:33], v[154:157], v[188:191], v[30:33]
	v_mfma_f32_16x16x32_bf16 v[22:25], v[146:149], v[204:207], v[22:25]
	v_mfma_f32_16x16x32_bf16 v[18:21], v[154:157], v[204:207], v[18:21]
	v_mfma_f32_16x16x32_bf16 v[6:9], v[146:149], v[220:223], v[6:9]
	v_mfma_f32_16x16x32_bf16 v[2:5], v[154:157], v[220:223], v[2:5]
	v_mfma_f32_16x16x32_bf16 v[54:57], v[150:153], v[178:181], v[54:57]
	v_mfma_f32_16x16x32_bf16 v[46:49], v[158:161], v[178:181], v[46:49]
	v_mfma_f32_16x16x32_bf16 v[38:41], v[150:153], v[200:203], v[38:41]
	v_mfma_f32_16x16x32_bf16 v[30:33], v[158:161], v[200:203], v[30:33]
	v_mfma_f32_16x16x32_bf16 v[22:25], v[150:153], v[216:219], v[22:25]
	v_mfma_f32_16x16x32_bf16 v[18:21], v[158:161], v[216:219], v[18:21]
	v_mfma_f32_16x16x32_bf16 v[6:9], v[150:153], v[224:227], v[6:9]
	v_mfma_f32_16x16x32_bf16 v[2:5], v[158:161], v[224:227], v[2:5]
	s_setprio 0
	s_barrier
	s_add_i32 s52, s52, 2
	s_add_u32 s6, s6, 0x100
	s_addc_u32 s7, s7, 0
	s_add_u32 s50, s50, 0x100
	s_addc_u32 s51, s51, 0
	s_cmp_gt_u32 s52, 29
	s_cbranch_scc0 .LBB0_67
	s_and_b64 vcc, exec, s[18:19]
	s_cbranch_vccz .LBB0_70
	s_barrier

.LBB0_116:
	s_add_u32 s30, s6, 0xfff80080
	s_addc_u32 s31, s7, -1
	s_add_i32 s52, 0, 0x10000
	s_cmp_eq_u32 s51, 28
	s_cselect_b32 s35, s23, s31
	s_cselect_b32 s34, s28, s30
	s_cselect_b32 s31, s21, s50
	s_cselect_b32 s30, s29, s49
	s_add_i32 s54, 0, 0x14000
	v_add_u32_e32 v78, s52, v240
	v_add_u32_e32 v98, s54, v240
	ds_read_b128 v[66:69], v78
	ds_read_b128 v[70:73], v78 offset:1024
	ds_read_b128 v[74:77], v78 offset:2048
	ds_read_b128 v[78:81], v78 offset:3072
	ds_read_b128 v[82:85], v98
	ds_read_b128 v[86:89], v98 offset:1024
	ds_read_b128 v[90:93], v98 offset:2048
	ds_read_b128 v[98:101], v98 offset:3072
	s_add_i32 m0, s37, 0xc000
	ds_read_b128 v[186:189], v241
	ds_read_b128 v[190:193], v241 offset:1024
	ds_read_b128 v[194:197], v241 offset:2048
	ds_read_b128 v[198:201], v241 offset:3072
	ds_read_b128 v[202:205], v241 offset:4096
	ds_read_b128 v[206:209], v241 offset:5120
	ds_read_b128 v[216:219], v241 offset:6144
	ds_read_b128 v[220:223], v241 offset:7168
	global_load_lds_dwordx4 v182, s[6:7]
	s_add_i32 m0, s37, 0xe000
	s_nop 0
	global_load_lds_dwordx4 v184, s[6:7]
	s_waitcnt vmcnt(8) lgkmcnt(0)
	s_barrier
	s_setprio 1
	v_mfma_f32_16x16x32_bf16 v[158:161], v[66:69], v[186:189], v[158:161]
	v_mfma_f32_16x16x32_bf16 v[154:157], v[74:77], v[186:189], v[154:157]
	v_mfma_f32_16x16x32_bf16 v[142:145], v[66:69], v[194:197], v[142:145]
	v_mfma_f32_16x16x32_bf16 v[138:141], v[74:77], v[194:197], v[138:141]
	v_mfma_f32_16x16x32_bf16 v[126:129], v[66:69], v[202:205], v[126:129]
	v_mfma_f32_16x16x32_bf16 v[122:125], v[74:77], v[202:205], v[122:125]
	v_mfma_f32_16x16x32_bf16 v[110:113], v[66:69], v[216:219], v[110:113]
	v_mfma_f32_16x16x32_bf16 v[106:109], v[74:77], v[216:219], v[106:109]
	v_mfma_f32_16x16x32_bf16 v[158:161], v[70:73], v[190:193], v[158:161]
	v_mfma_f32_16x16x32_bf16 v[154:157], v[78:81], v[190:193], v[154:157]
	v_mfma_f32_16x16x32_bf16 v[142:145], v[70:73], v[198:201], v[142:145]
	v_mfma_f32_16x16x32_bf16 v[138:141], v[78:81], v[198:201], v[138:141]
	v_mfma_f32_16x16x32_bf16 v[126:129], v[70:73], v[206:209], v[126:129]
	v_mfma_f32_16x16x32_bf16 v[122:125], v[78:81], v[206:209], v[122:125]
	v_mfma_f32_16x16x32_bf16 v[110:113], v[70:73], v[220:223], v[110:113]
	v_mfma_f32_16x16x32_bf16 v[106:109], v[78:81], v[220:223], v[106:109]
	v_mfma_f32_16x16x32_bf16 v[150:153], v[82:85], v[186:189], v[150:153]
	v_mfma_f32_16x16x32_bf16 v[146:149], v[90:93], v[186:189], v[146:149]
	v_mfma_f32_16x16x32_bf16 v[134:137], v[82:85], v[194:197], v[134:137]
	v_mfma_f32_16x16x32_bf16 v[130:133], v[90:93], v[194:197], v[130:133]
	v_mfma_f32_16x16x32_bf16 v[118:121], v[82:85], v[202:205], v[118:121]
	v_mfma_f32_16x16x32_bf16 v[114:117], v[90:93], v[202:205], v[114:117]
	v_mfma_f32_16x16x32_bf16 v[102:105], v[82:85], v[216:219], v[102:105]
	v_mfma_f32_16x16x32_bf16 v[94:97], v[90:93], v[216:219], v[94:97]
	v_mfma_f32_16x16x32_bf16 v[150:153], v[86:89], v[190:193], v[150:153]
	v_mfma_f32_16x16x32_bf16 v[146:149], v[98:101], v[190:193], v[146:149]
	v_mfma_f32_16x16x32_bf16 v[134:137], v[86:89], v[198:201], v[134:137]
	v_mfma_f32_16x16x32_bf16 v[130:133], v[98:101], v[198:201], v[130:133]
	v_mfma_f32_16x16x32_bf16 v[118:121], v[86:89], v[206:209], v[118:121]
	v_mfma_f32_16x16x32_bf16 v[114:117], v[98:101], v[206:209], v[114:117]
	v_mfma_f32_16x16x32_bf16 v[102:105], v[86:89], v[220:223], v[102:105]
	v_mfma_f32_16x16x32_bf16 v[94:97], v[98:101], v[220:223], v[94:97]
	s_setprio 0
	s_barrier
	s_add_i32 s52, s52, s36
	v_lshl_add_u64 v[212:213], s[30:31], 0, v[166:167]
	s_mov_b32 m0, s52
	ds_read_b128 v[186:189], v241 offset:16384
	ds_read_b128 v[190:193], v241 offset:17408
	ds_read_b128 v[194:197], v241 offset:18432
	ds_read_b128 v[198:201], v241 offset:19456
	ds_read_b128 v[202:205], v241 offset:20480
	ds_read_b128 v[206:209], v241 offset:21504
	ds_read_b128 v[216:219], v241 offset:22528
	ds_read_b128 v[220:223], v241 offset:23552
	global_load_lds_dwordx4 v[212:213], off
	s_add_i32 m0, s52, 0x2000
	s_add_u32 s52, s30, 0x80000
	v_lshl_add_u64 v[214:215], s[30:31], 0, v[162:163]
	s_addc_u32 s53, s31, 0
	s_add_i32 s54, s54, s36
	global_load_lds_dwordx4 v[214:215], off
	s_mov_b32 m0, s54
	v_lshl_add_u64 v[226:227], s[34:35], 0, v[164:165]
	global_load_lds_dwordx4 v166, s[52:53]
	s_add_i32 m0, s54, 0x2000
	s_nop 0
	global_load_lds_dwordx4 v162, s[52:53]
	v_lshl_add_u64 v[224:225], s[34:35], 0, v[168:169]
	s_mov_b32 m0, s37
	s_nop 0
	global_load_lds_dwordx4 v[224:225], off
	s_mov_b32 m0, s42
	s_nop 0
	global_load_lds_dwordx4 v[226:227], off
	s_waitcnt vmcnt(8) lgkmcnt(0)
	s_barrier
	s_setprio 1
	v_mfma_f32_16x16x32_bf16 v[62:65], v[66:69], v[186:189], v[62:65]
	v_mfma_f32_16x16x32_bf16 v[58:61], v[74:77], v[186:189], v[58:61]
	v_mfma_f32_16x16x32_bf16 v[46:49], v[66:69], v[194:197], v[46:49]
	v_mfma_f32_16x16x32_bf16 v[42:45], v[74:77], v[194:197], v[42:45]
	v_mfma_f32_16x16x32_bf16 v[30:33], v[66:69], v[202:205], v[30:33]
	v_mfma_f32_16x16x32_bf16 v[26:29], v[74:77], v[202:205], v[26:29]
	v_mfma_f32_16x16x32_bf16 v[14:17], v[66:69], v[216:219], v[14:17]
	v_mfma_f32_16x16x32_bf16 v[10:13], v[74:77], v[216:219], v[10:13]
	v_mfma_f32_16x16x32_bf16 v[62:65], v[70:73], v[190:193], v[62:65]
	v_mfma_f32_16x16x32_bf16 v[58:61], v[78:81], v[190:193], v[58:61]
	v_mfma_f32_16x16x32_bf16 v[46:49], v[70:73], v[198:201], v[46:49]
	v_mfma_f32_16x16x32_bf16 v[42:45], v[78:81], v[198:201], v[42:45]
	v_mfma_f32_16x16x32_bf16 v[30:33], v[70:73], v[206:209], v[30:33]
	v_mfma_f32_16x16x32_bf16 v[26:29], v[78:81], v[206:209], v[26:29]
	v_mfma_f32_16x16x32_bf16 v[14:17], v[70:73], v[220:223], v[14:17]
	v_mfma_f32_16x16x32_bf16 v[10:13], v[78:81], v[220:223], v[10:13]
	v_mfma_f32_16x16x32_bf16 v[54:57], v[82:85], v[186:189], v[54:57]
	v_mfma_f32_16x16x32_bf16 v[50:53], v[90:93], v[186:189], v[50:53]
	v_mfma_f32_16x16x32_bf16 v[38:41], v[82:85], v[194:197], v[38:41]
	v_mfma_f32_16x16x32_bf16 v[34:37], v[90:93], v[194:197], v[34:37]
	v_mfma_f32_16x16x32_bf16 v[22:25], v[82:85], v[202:205], v[22:25]
	v_mfma_f32_16x16x32_bf16 v[18:21], v[90:93], v[202:205], v[18:21]
	v_mfma_f32_16x16x32_bf16 v[6:9], v[82:85], v[216:219], v[6:9]
	v_mfma_f32_16x16x32_bf16 v[2:5], v[90:93], v[216:219], v[2:5]
	v_mfma_f32_16x16x32_bf16 v[54:57], v[86:89], v[190:193], v[54:57]
	v_mfma_f32_16x16x32_bf16 v[50:53], v[98:101], v[190:193], v[50:53]
	v_mfma_f32_16x16x32_bf16 v[38:41], v[86:89], v[198:201], v[38:41]
	v_mfma_f32_16x16x32_bf16 v[34:37], v[98:101], v[198:201], v[34:37]
	v_mfma_f32_16x16x32_bf16 v[22:25], v[86:89], v[206:209], v[22:25]
	v_mfma_f32_16x16x32_bf16 v[18:21], v[98:101], v[206:209], v[18:21]
	v_mfma_f32_16x16x32_bf16 v[6:9], v[86:89], v[220:223], v[6:9]
	v_mfma_f32_16x16x32_bf16 v[2:5], v[98:101], v[220:223], v[2:5]
	s_setprio 0
	s_barrier
	s_add_i32 s52, 0, 0x18000
	s_add_i32 s53, 0, 0x1c000
	v_add_u32_e32 v78, s52, v240
	v_add_u32_e32 v98, s53, v240
	ds_read_b128 v[66:69], v78
	ds_read_b128 v[70:73], v78 offset:1024
	ds_read_b128 v[74:77], v78 offset:2048
	ds_read_b128 v[78:81], v78 offset:3072
	ds_read_b128 v[82:85], v98
	ds_read_b128 v[86:89], v98 offset:1024
	ds_read_b128 v[90:93], v98 offset:2048
	ds_read_b128 v[98:101], v98 offset:3072
	s_add_u32 s34, s34, 0x80000
	s_addc_u32 s35, s35, 0
	s_mov_b32 m0, s43
	ds_read_b128 v[186:189], v241 offset:32768
	ds_read_b128 v[190:193], v241 offset:33792
	ds_read_b128 v[194:197], v241 offset:34816
	ds_read_b128 v[198:201], v241 offset:35840
	ds_read_b128 v[202:205], v241 offset:36864
	ds_read_b128 v[206:209], v241 offset:37888
	ds_read_b128 v[216:219], v241 offset:38912
	ds_read_b128 v[220:223], v241 offset:39936
	global_load_lds_dwordx4 v168, s[34:35]
	s_mov_b32 m0, s44
	s_nop 0
	global_load_lds_dwordx4 v164, s[34:35]
	s_waitcnt vmcnt(8) lgkmcnt(0)
	s_barrier
	s_setprio 1
	v_mfma_f32_16x16x32_bf16 v[158:161], v[66:69], v[186:189], v[158:161]
	v_mfma_f32_16x16x32_bf16 v[154:157], v[74:77], v[186:189], v[154:157]
	v_mfma_f32_16x16x32_bf16 v[142:145], v[66:69], v[194:197], v[142:145]
	v_mfma_f32_16x16x32_bf16 v[138:141], v[74:77], v[194:197], v[138:141]
	v_mfma_f32_16x16x32_bf16 v[126:129], v[66:69], v[202:205], v[126:129]
	v_mfma_f32_16x16x32_bf16 v[122:125], v[74:77], v[202:205], v[122:125]
	v_mfma_f32_16x16x32_bf16 v[110:113], v[66:69], v[216:219], v[110:113]
	v_mfma_f32_16x16x32_bf16 v[106:109], v[74:77], v[216:219], v[106:109]
	v_mfma_f32_16x16x32_bf16 v[158:161], v[70:73], v[190:193], v[158:161]
	v_mfma_f32_16x16x32_bf16 v[154:157], v[78:81], v[190:193], v[154:157]
	v_mfma_f32_16x16x32_bf16 v[142:145], v[70:73], v[198:201], v[142:145]
	v_mfma_f32_16x16x32_bf16 v[138:141], v[78:81], v[198:201], v[138:141]
	v_mfma_f32_16x16x32_bf16 v[126:129], v[70:73], v[206:209], v[126:129]
	v_mfma_f32_16x16x32_bf16 v[122:125], v[78:81], v[206:209], v[122:125]
	v_mfma_f32_16x16x32_bf16 v[110:113], v[70:73], v[220:223], v[110:113]
	v_mfma_f32_16x16x32_bf16 v[106:109], v[78:81], v[220:223], v[106:109]
	v_mfma_f32_16x16x32_bf16 v[150:153], v[82:85], v[186:189], v[150:153]
	v_mfma_f32_16x16x32_bf16 v[146:149], v[90:93], v[186:189], v[146:149]
	v_mfma_f32_16x16x32_bf16 v[134:137], v[82:85], v[194:197], v[134:137]
	v_mfma_f32_16x16x32_bf16 v[130:133], v[90:93], v[194:197], v[130:133]
	v_mfma_f32_16x16x32_bf16 v[118:121], v[82:85], v[202:205], v[118:121]
	v_mfma_f32_16x16x32_bf16 v[114:117], v[90:93], v[202:205], v[114:117]
	v_mfma_f32_16x16x32_bf16 v[102:105], v[82:85], v[216:219], v[102:105]
	v_mfma_f32_16x16x32_bf16 v[94:97], v[90:93], v[216:219], v[94:97]
	v_mfma_f32_16x16x32_bf16 v[150:153], v[86:89], v[190:193], v[150:153]
	v_mfma_f32_16x16x32_bf16 v[146:149], v[98:101], v[190:193], v[146:149]
	v_mfma_f32_16x16x32_bf16 v[134:137], v[86:89], v[198:201], v[134:137]
	v_mfma_f32_16x16x32_bf16 v[130:133], v[98:101], v[198:201], v[130:133]
	v_mfma_f32_16x16x32_bf16 v[118:121], v[86:89], v[206:209], v[118:121]
	v_mfma_f32_16x16x32_bf16 v[114:117], v[98:101], v[206:209], v[114:117]
	v_mfma_f32_16x16x32_bf16 v[102:105], v[86:89], v[220:223], v[102:105]
	v_mfma_f32_16x16x32_bf16 v[94:97], v[98:101], v[220:223], v[94:97]
	s_setprio 0
	s_barrier
	s_add_i32 s34, s52, s36
	v_lshl_add_u64 v[212:213], v[212:213], 0, s[64:65]
	s_mov_b32 m0, s34
	ds_read_b128 v[186:189], v241 offset:49152
	ds_read_b128 v[190:193], v241 offset:50176
	ds_read_b128 v[194:197], v241 offset:51200
	ds_read_b128 v[198:201], v241 offset:52224
	ds_read_b128 v[202:205], v241 offset:53248
	ds_read_b128 v[206:209], v241 offset:54272
	ds_read_b128 v[216:219], v241 offset:55296
	ds_read_b128 v[220:223], v241 offset:56320
	global_load_lds_dwordx4 v[212:213], off
	s_add_i32 m0, s34, 0x2000
	s_add_u32 s30, s30, 0x80080
	v_lshl_add_u64 v[212:213], v[214:215], 0, s[64:65]
	s_addc_u32 s31, s31, 0
	s_add_i32 s34, s53, s36
	global_load_lds_dwordx4 v[212:213], off
	s_mov_b32 m0, s34
	s_nop 0
	global_load_lds_dwordx4 v166, s[30:31]
	s_add_i32 m0, s34, 0x2000
	s_nop 0
	global_load_lds_dwordx4 v162, s[30:31]
	v_lshl_add_u64 v[212:213], v[224:225], 0, s[64:65]
	s_mov_b32 m0, s46
	s_nop 0
	global_load_lds_dwordx4 v[212:213], off
	v_lshl_add_u64 v[212:213], v[226:227], 0, s[64:65]
	s_mov_b32 m0, s47
	s_nop 0
	global_load_lds_dwordx4 v[212:213], off
	s_waitcnt vmcnt(8) lgkmcnt(0)
	s_barrier
	s_setprio 1
	v_mfma_f32_16x16x32_bf16 v[62:65], v[66:69], v[186:189], v[62:65]
	v_mfma_f32_16x16x32_bf16 v[58:61], v[74:77], v[186:189], v[58:61]
	v_mfma_f32_16x16x32_bf16 v[46:49], v[66:69], v[194:197], v[46:49]
	v_mfma_f32_16x16x32_bf16 v[42:45], v[74:77], v[194:197], v[42:45]
	v_mfma_f32_16x16x32_bf16 v[30:33], v[66:69], v[202:205], v[30:33]
	v_mfma_f32_16x16x32_bf16 v[26:29], v[74:77], v[202:205], v[26:29]
	v_mfma_f32_16x16x32_bf16 v[14:17], v[66:69], v[216:219], v[14:17]
	v_mfma_f32_16x16x32_bf16 v[10:13], v[74:77], v[216:219], v[10:13]
	v_mfma_f32_16x16x32_bf16 v[62:65], v[70:73], v[190:193], v[62:65]
	v_mfma_f32_16x16x32_bf16 v[58:61], v[78:81], v[190:193], v[58:61]
	v_mfma_f32_16x16x32_bf16 v[46:49], v[70:73], v[198:201], v[46:49]
	v_mfma_f32_16x16x32_bf16 v[42:45], v[78:81], v[198:201], v[42:45]
	v_mfma_f32_16x16x32_bf16 v[30:33], v[70:73], v[206:209], v[30:33]
	v_mfma_f32_16x16x32_bf16 v[26:29], v[78:81], v[206:209], v[26:29]
	v_mfma_f32_16x16x32_bf16 v[14:17], v[70:73], v[220:223], v[14:17]
	v_mfma_f32_16x16x32_bf16 v[10:13], v[78:81], v[220:223], v[10:13]
	v_mfma_f32_16x16x32_bf16 v[54:57], v[82:85], v[186:189], v[54:57]
	v_mfma_f32_16x16x32_bf16 v[50:53], v[90:93], v[186:189], v[50:53]
	v_mfma_f32_16x16x32_bf16 v[38:41], v[82:85], v[194:197], v[38:41]
	v_mfma_f32_16x16x32_bf16 v[34:37], v[90:93], v[194:197], v[34:37]
	v_mfma_f32_16x16x32_bf16 v[22:25], v[82:85], v[202:205], v[22:25]
	v_mfma_f32_16x16x32_bf16 v[18:21], v[90:93], v[202:205], v[18:21]
	v_mfma_f32_16x16x32_bf16 v[6:9], v[82:85], v[216:219], v[6:9]
	v_mfma_f32_16x16x32_bf16 v[2:5], v[90:93], v[216:219], v[2:5]
	v_mfma_f32_16x16x32_bf16 v[54:57], v[86:89], v[190:193], v[54:57]
	v_mfma_f32_16x16x32_bf16 v[50:53], v[98:101], v[190:193], v[50:53]
	v_mfma_f32_16x16x32_bf16 v[38:41], v[86:89], v[198:201], v[38:41]
	v_mfma_f32_16x16x32_bf16 v[34:37], v[98:101], v[198:201], v[34:37]
	v_mfma_f32_16x16x32_bf16 v[22:25], v[86:89], v[206:209], v[22:25]
	v_mfma_f32_16x16x32_bf16 v[18:21], v[98:101], v[206:209], v[18:21]
	v_mfma_f32_16x16x32_bf16 v[6:9], v[86:89], v[220:223], v[6:9]
	v_mfma_f32_16x16x32_bf16 v[2:5], v[98:101], v[220:223], v[2:5]
	s_setprio 0
	s_barrier
	s_add_i32 s51, s51, 2
	s_add_u32 s6, s6, 0x100
	s_addc_u32 s7, s7, 0
	s_add_u32 s49, s49, 0x100
	s_addc_u32 s50, s50, 0
	s_cmp_gt_u32 s51, 29
	s_cbranch_scc0 .LBB0_116
	s_and_b64 vcc, exec, s[18:19]
	s_cbranch_vccz .LBB0_119
	s_barrier

.LBB0_226:
	s_add_u32 s30, s8, 0xfff80080
	s_addc_u32 s31, s9, -1
	s_add_i32 s54, 0, 0x10000
	s_cmp_eq_u32 s53, 28
	s_cselect_b32 s35, s23, s31
	s_cselect_b32 s34, s28, s30
	s_cselect_b32 s31, s21, s52
	s_cselect_b32 s30, s29, s51
	s_add_i32 s56, 0, 0x14000
	v_add_u32_e32 v160, s54, v141
	v_add_u32_e32 v176, s56, v141
	ds_read_b128 v[148:151], v160
	ds_read_b128 v[152:155], v160 offset:1024
	ds_read_b128 v[156:159], v160 offset:2048
	ds_read_b128 v[160:163], v160 offset:3072
	ds_read_b128 v[164:167], v176
	ds_read_b128 v[168:171], v176 offset:1024
	ds_read_b128 v[172:175], v176 offset:2048
	ds_read_b128 v[176:179], v176 offset:3072
	s_add_i32 m0, s41, 0xc000
	ds_read_b128 v[180:183], v238
	ds_read_b128 v[184:187], v238 offset:1024
	ds_read_b128 v[188:191], v238 offset:2048
	ds_read_b128 v[192:195], v238 offset:3072
	ds_read_b128 v[196:199], v238 offset:4096
	ds_read_b128 v[200:203], v238 offset:5120
	ds_read_b128 v[204:207], v238 offset:6144
	ds_read_b128 v[216:219], v238 offset:7168
	global_load_lds_dwordx4 v144, s[8:9]
	s_add_i32 m0, s41, 0xe000
	s_nop 0
	global_load_lds_dwordx4 v146, s[8:9]
	s_waitcnt vmcnt(8) lgkmcnt(0)
	s_barrier
	s_setprio 1
	v_mfma_f32_16x16x32_bf16 v[126:129], v[148:151], v[180:183], v[126:129]
	v_mfma_f32_16x16x32_bf16 v[122:125], v[156:159], v[180:183], v[122:125]
	v_mfma_f32_16x16x32_bf16 v[110:113], v[148:151], v[188:191], v[110:113]
	v_mfma_f32_16x16x32_bf16 v[106:109], v[156:159], v[188:191], v[106:109]
	v_mfma_f32_16x16x32_bf16 v[94:97], v[148:151], v[196:199], v[94:97]
	v_mfma_f32_16x16x32_bf16 v[90:93], v[156:159], v[196:199], v[90:93]
	v_mfma_f32_16x16x32_bf16 v[78:81], v[148:151], v[204:207], v[78:81]
	v_mfma_f32_16x16x32_bf16 v[74:77], v[156:159], v[204:207], v[74:77]
	v_mfma_f32_16x16x32_bf16 v[126:129], v[152:155], v[184:187], v[126:129]
	v_mfma_f32_16x16x32_bf16 v[122:125], v[160:163], v[184:187], v[122:125]
	v_mfma_f32_16x16x32_bf16 v[110:113], v[152:155], v[192:195], v[110:113]
	v_mfma_f32_16x16x32_bf16 v[106:109], v[160:163], v[192:195], v[106:109]
	v_mfma_f32_16x16x32_bf16 v[94:97], v[152:155], v[200:203], v[94:97]
	v_mfma_f32_16x16x32_bf16 v[90:93], v[160:163], v[200:203], v[90:93]
	v_mfma_f32_16x16x32_bf16 v[78:81], v[152:155], v[216:219], v[78:81]
	v_mfma_f32_16x16x32_bf16 v[74:77], v[160:163], v[216:219], v[74:77]
	v_mfma_f32_16x16x32_bf16 v[118:121], v[164:167], v[180:183], v[118:121]
	v_mfma_f32_16x16x32_bf16 v[114:117], v[172:175], v[180:183], v[114:117]
	v_mfma_f32_16x16x32_bf16 v[102:105], v[164:167], v[188:191], v[102:105]
	v_mfma_f32_16x16x32_bf16 v[98:101], v[172:175], v[188:191], v[98:101]
	v_mfma_f32_16x16x32_bf16 v[86:89], v[164:167], v[196:199], v[86:89]
	v_mfma_f32_16x16x32_bf16 v[82:85], v[172:175], v[196:199], v[82:85]
	v_mfma_f32_16x16x32_bf16 v[70:73], v[164:167], v[204:207], v[70:73]
	v_mfma_f32_16x16x32_bf16 v[66:69], v[172:175], v[204:207], v[66:69]
	v_mfma_f32_16x16x32_bf16 v[118:121], v[168:171], v[184:187], v[118:121]
	v_mfma_f32_16x16x32_bf16 v[114:117], v[176:179], v[184:187], v[114:117]
	v_mfma_f32_16x16x32_bf16 v[102:105], v[168:171], v[192:195], v[102:105]
	v_mfma_f32_16x16x32_bf16 v[98:101], v[176:179], v[192:195], v[98:101]
	v_mfma_f32_16x16x32_bf16 v[86:89], v[168:171], v[200:203], v[86:89]
	v_mfma_f32_16x16x32_bf16 v[82:85], v[176:179], v[200:203], v[82:85]
	v_mfma_f32_16x16x32_bf16 v[70:73], v[168:171], v[216:219], v[70:73]
	v_mfma_f32_16x16x32_bf16 v[66:69], v[176:179], v[216:219], v[66:69]
	s_setprio 0
	s_barrier
	s_add_i32 s54, s54, s40
	v_lshl_add_u64 v[208:209], s[30:31], 0, v[134:135]
	s_mov_b32 m0, s54
	ds_read_b128 v[180:183], v238 offset:16384
	ds_read_b128 v[184:187], v238 offset:17408
	ds_read_b128 v[188:191], v238 offset:18432
	ds_read_b128 v[192:195], v238 offset:19456
	ds_read_b128 v[196:199], v238 offset:20480
	ds_read_b128 v[200:203], v238 offset:21504
	ds_read_b128 v[204:207], v238 offset:22528
	ds_read_b128 v[216:219], v238 offset:23552
	global_load_lds_dwordx4 v[208:209], off
	s_add_i32 m0, s54, 0x2000
	s_add_u32 s54, s30, 0x80000
	v_lshl_add_u64 v[212:213], s[30:31], 0, v[130:131]
	s_addc_u32 s55, s31, 0
	s_add_i32 s56, s56, s40
	global_load_lds_dwordx4 v[212:213], off
	s_mov_b32 m0, s56
	v_lshl_add_u64 v[220:221], s[34:35], 0, v[132:133]
	global_load_lds_dwordx4 v134, s[54:55]
	s_add_i32 m0, s56, 0x2000
	s_nop 0
	global_load_lds_dwordx4 v130, s[54:55]
	v_lshl_add_u64 v[214:215], s[34:35], 0, v[136:137]
	s_mov_b32 m0, s41
	s_nop 0
	global_load_lds_dwordx4 v[214:215], off
	s_mov_b32 m0, s42
	s_nop 0
	global_load_lds_dwordx4 v[220:221], off
	s_waitcnt vmcnt(8) lgkmcnt(0)
	s_barrier
	s_setprio 1
	v_mfma_f32_16x16x32_bf16 v[62:65], v[148:151], v[180:183], v[62:65]
	v_mfma_f32_16x16x32_bf16 v[58:61], v[156:159], v[180:183], v[58:61]
	v_mfma_f32_16x16x32_bf16 v[46:49], v[148:151], v[188:191], v[46:49]
	v_mfma_f32_16x16x32_bf16 v[42:45], v[156:159], v[188:191], v[42:45]
	v_mfma_f32_16x16x32_bf16 v[30:33], v[148:151], v[196:199], v[30:33]
	v_mfma_f32_16x16x32_bf16 v[26:29], v[156:159], v[196:199], v[26:29]
	v_mfma_f32_16x16x32_bf16 v[14:17], v[148:151], v[204:207], v[14:17]
	v_mfma_f32_16x16x32_bf16 v[10:13], v[156:159], v[204:207], v[10:13]
	v_mfma_f32_16x16x32_bf16 v[62:65], v[152:155], v[184:187], v[62:65]
	v_mfma_f32_16x16x32_bf16 v[58:61], v[160:163], v[184:187], v[58:61]
	v_mfma_f32_16x16x32_bf16 v[46:49], v[152:155], v[192:195], v[46:49]
	v_mfma_f32_16x16x32_bf16 v[42:45], v[160:163], v[192:195], v[42:45]
	v_mfma_f32_16x16x32_bf16 v[30:33], v[152:155], v[200:203], v[30:33]
	v_mfma_f32_16x16x32_bf16 v[26:29], v[160:163], v[200:203], v[26:29]
	v_mfma_f32_16x16x32_bf16 v[14:17], v[152:155], v[216:219], v[14:17]
	v_mfma_f32_16x16x32_bf16 v[10:13], v[160:163], v[216:219], v[10:13]
	v_mfma_f32_16x16x32_bf16 v[54:57], v[164:167], v[180:183], v[54:57]
	v_mfma_f32_16x16x32_bf16 v[50:53], v[172:175], v[180:183], v[50:53]
	v_mfma_f32_16x16x32_bf16 v[38:41], v[164:167], v[188:191], v[38:41]
	v_mfma_f32_16x16x32_bf16 v[34:37], v[172:175], v[188:191], v[34:37]
	v_mfma_f32_16x16x32_bf16 v[22:25], v[164:167], v[196:199], v[22:25]
	v_mfma_f32_16x16x32_bf16 v[18:21], v[172:175], v[196:199], v[18:21]
	v_mfma_f32_16x16x32_bf16 v[6:9], v[164:167], v[204:207], v[6:9]
	v_mfma_f32_16x16x32_bf16 v[2:5], v[172:175], v[204:207], v[2:5]
	v_mfma_f32_16x16x32_bf16 v[54:57], v[168:171], v[184:187], v[54:57]
	v_mfma_f32_16x16x32_bf16 v[50:53], v[176:179], v[184:187], v[50:53]
	v_mfma_f32_16x16x32_bf16 v[38:41], v[168:171], v[192:195], v[38:41]
	v_mfma_f32_16x16x32_bf16 v[34:37], v[176:179], v[192:195], v[34:37]
	v_mfma_f32_16x16x32_bf16 v[22:25], v[168:171], v[200:203], v[22:25]
	v_mfma_f32_16x16x32_bf16 v[18:21], v[176:179], v[200:203], v[18:21]
	v_mfma_f32_16x16x32_bf16 v[6:9], v[168:171], v[216:219], v[6:9]
	v_mfma_f32_16x16x32_bf16 v[2:5], v[176:179], v[216:219], v[2:5]
	s_setprio 0
	s_barrier
	s_add_i32 s54, 0, 0x18000
	s_add_i32 s55, 0, 0x1c000
	v_add_u32_e32 v160, s54, v141
	v_add_u32_e32 v176, s55, v141
	ds_read_b128 v[148:151], v160
	ds_read_b128 v[152:155], v160 offset:1024
	ds_read_b128 v[156:159], v160 offset:2048
	ds_read_b128 v[160:163], v160 offset:3072
	ds_read_b128 v[164:167], v176
	ds_read_b128 v[168:171], v176 offset:1024
	ds_read_b128 v[172:175], v176 offset:2048
	ds_read_b128 v[176:179], v176 offset:3072
	s_add_u32 s34, s34, 0x80000
	s_addc_u32 s35, s35, 0
	s_mov_b32 m0, s43
	ds_read_b128 v[180:183], v238 offset:32768
	ds_read_b128 v[184:187], v238 offset:33792
	ds_read_b128 v[188:191], v238 offset:34816
	ds_read_b128 v[192:195], v238 offset:35840
	ds_read_b128 v[196:199], v238 offset:36864
	ds_read_b128 v[200:203], v238 offset:37888
	ds_read_b128 v[204:207], v238 offset:38912
	ds_read_b128 v[216:219], v238 offset:39936
	global_load_lds_dwordx4 v136, s[34:35]
	s_mov_b32 m0, s44
	s_nop 0
	global_load_lds_dwordx4 v132, s[34:35]
	s_waitcnt vmcnt(8) lgkmcnt(0)
	s_barrier
	s_setprio 1
	v_mfma_f32_16x16x32_bf16 v[126:129], v[148:151], v[180:183], v[126:129]
	v_mfma_f32_16x16x32_bf16 v[122:125], v[156:159], v[180:183], v[122:125]
	v_mfma_f32_16x16x32_bf16 v[110:113], v[148:151], v[188:191], v[110:113]
	v_mfma_f32_16x16x32_bf16 v[106:109], v[156:159], v[188:191], v[106:109]
	v_mfma_f32_16x16x32_bf16 v[94:97], v[148:151], v[196:199], v[94:97]
	v_mfma_f32_16x16x32_bf16 v[90:93], v[156:159], v[196:199], v[90:93]
	v_mfma_f32_16x16x32_bf16 v[78:81], v[148:151], v[204:207], v[78:81]
	v_mfma_f32_16x16x32_bf16 v[74:77], v[156:159], v[204:207], v[74:77]
	v_mfma_f32_16x16x32_bf16 v[126:129], v[152:155], v[184:187], v[126:129]
	v_mfma_f32_16x16x32_bf16 v[122:125], v[160:163], v[184:187], v[122:125]
	v_mfma_f32_16x16x32_bf16 v[110:113], v[152:155], v[192:195], v[110:113]
	v_mfma_f32_16x16x32_bf16 v[106:109], v[160:163], v[192:195], v[106:109]
	v_mfma_f32_16x16x32_bf16 v[94:97], v[152:155], v[200:203], v[94:97]
	v_mfma_f32_16x16x32_bf16 v[90:93], v[160:163], v[200:203], v[90:93]
	v_mfma_f32_16x16x32_bf16 v[78:81], v[152:155], v[216:219], v[78:81]
	v_mfma_f32_16x16x32_bf16 v[74:77], v[160:163], v[216:219], v[74:77]
	v_mfma_f32_16x16x32_bf16 v[118:121], v[164:167], v[180:183], v[118:121]
	v_mfma_f32_16x16x32_bf16 v[114:117], v[172:175], v[180:183], v[114:117]
	v_mfma_f32_16x16x32_bf16 v[102:105], v[164:167], v[188:191], v[102:105]
	v_mfma_f32_16x16x32_bf16 v[98:101], v[172:175], v[188:191], v[98:101]
	v_mfma_f32_16x16x32_bf16 v[86:89], v[164:167], v[196:199], v[86:89]
	v_mfma_f32_16x16x32_bf16 v[82:85], v[172:175], v[196:199], v[82:85]
	v_mfma_f32_16x16x32_bf16 v[70:73], v[164:167], v[204:207], v[70:73]
	v_mfma_f32_16x16x32_bf16 v[66:69], v[172:175], v[204:207], v[66:69]
	v_mfma_f32_16x16x32_bf16 v[118:121], v[168:171], v[184:187], v[118:121]
	v_mfma_f32_16x16x32_bf16 v[114:117], v[176:179], v[184:187], v[114:117]
	v_mfma_f32_16x16x32_bf16 v[102:105], v[168:171], v[192:195], v[102:105]
	v_mfma_f32_16x16x32_bf16 v[98:101], v[176:179], v[192:195], v[98:101]
	v_mfma_f32_16x16x32_bf16 v[86:89], v[168:171], v[200:203], v[86:89]
	v_mfma_f32_16x16x32_bf16 v[82:85], v[176:179], v[200:203], v[82:85]
	v_mfma_f32_16x16x32_bf16 v[70:73], v[168:171], v[216:219], v[70:73]
	v_mfma_f32_16x16x32_bf16 v[66:69], v[176:179], v[216:219], v[66:69]
	s_setprio 0
	s_barrier
	s_add_i32 s34, s54, s40
	v_lshl_add_u64 v[208:209], v[208:209], 0, s[64:65]
	s_mov_b32 m0, s34
	ds_read_b128 v[180:183], v238 offset:49152
	ds_read_b128 v[184:187], v238 offset:50176
	ds_read_b128 v[188:191], v238 offset:51200
	ds_read_b128 v[192:195], v238 offset:52224
	ds_read_b128 v[196:199], v238 offset:53248
	ds_read_b128 v[200:203], v238 offset:54272
	ds_read_b128 v[204:207], v238 offset:55296
	ds_read_b128 v[216:219], v238 offset:56320
	global_load_lds_dwordx4 v[208:209], off
	s_add_i32 m0, s34, 0x2000
	s_add_u32 s30, s30, 0x80080
	v_lshl_add_u64 v[208:209], v[212:213], 0, s[64:65]
	s_addc_u32 s31, s31, 0
	s_add_i32 s34, s55, s40
	global_load_lds_dwordx4 v[208:209], off
	s_mov_b32 m0, s34
	s_nop 0
	global_load_lds_dwordx4 v134, s[30:31]
	s_add_i32 m0, s34, 0x2000
	s_nop 0
	global_load_lds_dwordx4 v130, s[30:31]
	v_lshl_add_u64 v[208:209], v[214:215], 0, s[64:65]
	s_mov_b32 m0, s46
	s_nop 0
	global_load_lds_dwordx4 v[208:209], off
	v_lshl_add_u64 v[208:209], v[220:221], 0, s[64:65]
	s_mov_b32 m0, s47
	s_nop 0
	global_load_lds_dwordx4 v[208:209], off
	s_waitcnt vmcnt(8) lgkmcnt(0)
	s_barrier
	s_setprio 1
	v_mfma_f32_16x16x32_bf16 v[62:65], v[148:151], v[180:183], v[62:65]
	v_mfma_f32_16x16x32_bf16 v[58:61], v[156:159], v[180:183], v[58:61]
	v_mfma_f32_16x16x32_bf16 v[46:49], v[148:151], v[188:191], v[46:49]
	v_mfma_f32_16x16x32_bf16 v[42:45], v[156:159], v[188:191], v[42:45]
	v_mfma_f32_16x16x32_bf16 v[30:33], v[148:151], v[196:199], v[30:33]
	v_mfma_f32_16x16x32_bf16 v[26:29], v[156:159], v[196:199], v[26:29]
	v_mfma_f32_16x16x32_bf16 v[14:17], v[148:151], v[204:207], v[14:17]
	v_mfma_f32_16x16x32_bf16 v[10:13], v[156:159], v[204:207], v[10:13]
	v_mfma_f32_16x16x32_bf16 v[62:65], v[152:155], v[184:187], v[62:65]
	v_mfma_f32_16x16x32_bf16 v[58:61], v[160:163], v[184:187], v[58:61]
	v_mfma_f32_16x16x32_bf16 v[46:49], v[152:155], v[192:195], v[46:49]
	v_mfma_f32_16x16x32_bf16 v[42:45], v[160:163], v[192:195], v[42:45]
	v_mfma_f32_16x16x32_bf16 v[30:33], v[152:155], v[200:203], v[30:33]
	v_mfma_f32_16x16x32_bf16 v[26:29], v[160:163], v[200:203], v[26:29]
	v_mfma_f32_16x16x32_bf16 v[14:17], v[152:155], v[216:219], v[14:17]
	v_mfma_f32_16x16x32_bf16 v[10:13], v[160:163], v[216:219], v[10:13]
	v_mfma_f32_16x16x32_bf16 v[54:57], v[164:167], v[180:183], v[54:57]
	v_mfma_f32_16x16x32_bf16 v[50:53], v[172:175], v[180:183], v[50:53]
	v_mfma_f32_16x16x32_bf16 v[38:41], v[164:167], v[188:191], v[38:41]
	v_mfma_f32_16x16x32_bf16 v[34:37], v[172:175], v[188:191], v[34:37]
	v_mfma_f32_16x16x32_bf16 v[22:25], v[164:167], v[196:199], v[22:25]
	v_mfma_f32_16x16x32_bf16 v[18:21], v[172:175], v[196:199], v[18:21]
	v_mfma_f32_16x16x32_bf16 v[6:9], v[164:167], v[204:207], v[6:9]
	v_mfma_f32_16x16x32_bf16 v[2:5], v[172:175], v[204:207], v[2:5]
	v_mfma_f32_16x16x32_bf16 v[54:57], v[168:171], v[184:187], v[54:57]
	v_mfma_f32_16x16x32_bf16 v[50:53], v[176:179], v[184:187], v[50:53]
	v_mfma_f32_16x16x32_bf16 v[38:41], v[168:171], v[192:195], v[38:41]
	v_mfma_f32_16x16x32_bf16 v[34:37], v[176:179], v[192:195], v[34:37]
	v_mfma_f32_16x16x32_bf16 v[22:25], v[168:171], v[200:203], v[22:25]
	v_mfma_f32_16x16x32_bf16 v[18:21], v[176:179], v[200:203], v[18:21]
	v_mfma_f32_16x16x32_bf16 v[6:9], v[168:171], v[216:219], v[6:9]
	v_mfma_f32_16x16x32_bf16 v[2:5], v[176:179], v[216:219], v[2:5]
	s_setprio 0
	s_barrier
	s_add_i32 s53, s53, 2
	s_add_u32 s8, s8, 0x100
	s_addc_u32 s9, s9, 0
	s_add_u32 s51, s51, 0x100
	s_addc_u32 s52, s52, 0
	s_cmp_gt_u32 s53, 29
	s_cbranch_scc0 .LBB0_226
	s_and_b64 vcc, exec, s[18:19]
	s_cbranch_vccz .LBB0_229
	s_barrier

.LBB0_956:
	s_add_u32 s10, s34, 0x100
	s_addc_u32 s11, s35, 0
	s_add_i32 s63, 0, 0x10000
	s_cmp_eq_u32 s62, 28
	s_cselect_b32 s47, s2, s11
	s_cselect_b32 s46, s3, s10
	s_cselect_b32 s43, s31, s61
	s_cselect_b32 s42, s37, s60
	s_add_i32 s66, 0, 0x14000
	v_add_u32_e32 v78, s63, v251
	v_add_u32_e32 v94, s66, v251
	ds_read_b128 v[66:69], v78
	ds_read_b128 v[70:73], v78 offset:1024
	ds_read_b128 v[74:77], v78 offset:2048
	ds_read_b128 v[78:81], v78 offset:3072
	ds_read_b128 v[82:85], v94
	ds_read_b128 v[86:89], v94 offset:1024
	ds_read_b128 v[90:93], v94 offset:2048
	ds_read_b128 v[94:97], v94 offset:3072
	v_lshl_add_u64 v[194:195], s[34:35], 0, v[218:219]
	s_add_i32 m0, s51, 0xc000
	ds_read_b128 v[162:165], v244
	ds_read_b128 v[166:169], v244 offset:1024
	ds_read_b128 v[170:173], v244 offset:2048
	ds_read_b128 v[174:177], v244 offset:3072
	ds_read_b128 v[178:181], v244 offset:4096
	ds_read_b128 v[182:185], v244 offset:5120
	ds_read_b128 v[186:189], v244 offset:6144
	ds_read_b128 v[190:193], v244 offset:7168
	global_load_lds_dwordx4 v[194:195], off
	v_lshl_add_u64 v[194:195], s[34:35], 0, v[220:221]
	s_add_i32 m0, s51, 0xe000
	s_nop 0
	global_load_lds_dwordx4 v[194:195], off
	s_waitcnt vmcnt(8) lgkmcnt(0)
	s_barrier
	s_setprio 1
	v_mfma_f32_16x16x32_bf16 v[158:161], v[66:69], v[162:165], v[158:161]
	v_mfma_f32_16x16x32_bf16 v[154:157], v[74:77], v[162:165], v[154:157]
	v_mfma_f32_16x16x32_bf16 v[142:145], v[66:69], v[170:173], v[142:145]
	v_mfma_f32_16x16x32_bf16 v[138:141], v[74:77], v[170:173], v[138:141]
	v_mfma_f32_16x16x32_bf16 v[126:129], v[66:69], v[178:181], v[126:129]
	v_mfma_f32_16x16x32_bf16 v[122:125], v[74:77], v[178:181], v[122:125]
	v_mfma_f32_16x16x32_bf16 v[110:113], v[66:69], v[186:189], v[110:113]
	v_mfma_f32_16x16x32_bf16 v[106:109], v[74:77], v[186:189], v[106:109]
	v_mfma_f32_16x16x32_bf16 v[158:161], v[70:73], v[166:169], v[158:161]
	v_mfma_f32_16x16x32_bf16 v[154:157], v[78:81], v[166:169], v[154:157]
	v_mfma_f32_16x16x32_bf16 v[142:145], v[70:73], v[174:177], v[142:145]
	v_mfma_f32_16x16x32_bf16 v[138:141], v[78:81], v[174:177], v[138:141]
	v_mfma_f32_16x16x32_bf16 v[126:129], v[70:73], v[182:185], v[126:129]
	v_mfma_f32_16x16x32_bf16 v[122:125], v[78:81], v[182:185], v[122:125]
	v_mfma_f32_16x16x32_bf16 v[110:113], v[70:73], v[190:193], v[110:113]
	v_mfma_f32_16x16x32_bf16 v[106:109], v[78:81], v[190:193], v[106:109]
	v_mfma_f32_16x16x32_bf16 v[150:153], v[82:85], v[162:165], v[150:153]
	v_mfma_f32_16x16x32_bf16 v[146:149], v[90:93], v[162:165], v[146:149]
	v_mfma_f32_16x16x32_bf16 v[134:137], v[82:85], v[170:173], v[134:137]
	v_mfma_f32_16x16x32_bf16 v[130:133], v[90:93], v[170:173], v[130:133]
	v_mfma_f32_16x16x32_bf16 v[118:121], v[82:85], v[178:181], v[118:121]
	v_mfma_f32_16x16x32_bf16 v[114:117], v[90:93], v[178:181], v[114:117]
	v_mfma_f32_16x16x32_bf16 v[102:105], v[82:85], v[186:189], v[102:105]
	v_mfma_f32_16x16x32_bf16 v[98:101], v[90:93], v[186:189], v[98:101]
	v_mfma_f32_16x16x32_bf16 v[150:153], v[86:89], v[166:169], v[150:153]
	v_mfma_f32_16x16x32_bf16 v[146:149], v[94:97], v[166:169], v[146:149]
	v_mfma_f32_16x16x32_bf16 v[134:137], v[86:89], v[174:177], v[134:137]
	v_mfma_f32_16x16x32_bf16 v[130:133], v[94:97], v[174:177], v[130:133]
	v_mfma_f32_16x16x32_bf16 v[118:121], v[86:89], v[182:185], v[118:121]
	v_mfma_f32_16x16x32_bf16 v[114:117], v[94:97], v[182:185], v[114:117]
	v_mfma_f32_16x16x32_bf16 v[102:105], v[86:89], v[190:193], v[102:105]
	v_mfma_f32_16x16x32_bf16 v[98:101], v[94:97], v[190:193], v[98:101]
	s_setprio 0
	s_barrier
	s_add_i32 s34, s63, s44
	v_lshl_add_u64 v[194:195], s[42:43], 0, v[210:211]
	s_mov_b32 m0, s34
	ds_read_b128 v[162:165], v244 offset:16384
	ds_read_b128 v[166:169], v244 offset:17408
	ds_read_b128 v[170:173], v244 offset:18432
	ds_read_b128 v[174:177], v244 offset:19456
	ds_read_b128 v[178:181], v244 offset:20480
	ds_read_b128 v[182:185], v244 offset:21504
	ds_read_b128 v[186:189], v244 offset:22528
	ds_read_b128 v[190:193], v244 offset:23552
	global_load_lds_dwordx4 v[194:195], off
	s_add_i32 m0, s34, 0x2000
	s_add_u32 s34, s42, 0x80000
	v_lshl_add_u64 v[196:197], s[42:43], 0, v[216:217]
	s_addc_u32 s35, s43, 0
	s_add_i32 s63, s66, s44
	global_load_lds_dwordx4 v[196:197], off
	s_mov_b32 m0, s63
	v_lshl_add_u64 v[200:201], s[46:47], 0, v[216:217]
	global_load_lds_dwordx4 v210, s[34:35]
	s_add_i32 m0, s63, 0x2000
	s_nop 0
	global_load_lds_dwordx4 v216, s[34:35]
	v_lshl_add_u64 v[198:199], s[46:47], 0, v[210:211]
	s_mov_b32 m0, s51
	s_nop 0
	global_load_lds_dwordx4 v[198:199], off
	s_mov_b32 m0, s52
	s_nop 0
	global_load_lds_dwordx4 v[200:201], off
	s_waitcnt vmcnt(8) lgkmcnt(0)
	s_barrier
	s_setprio 1
	v_mfma_f32_16x16x32_bf16 v[62:65], v[66:69], v[162:165], v[62:65]
	v_mfma_f32_16x16x32_bf16 v[58:61], v[74:77], v[162:165], v[58:61]
	v_mfma_f32_16x16x32_bf16 v[46:49], v[66:69], v[170:173], v[46:49]
	v_mfma_f32_16x16x32_bf16 v[42:45], v[74:77], v[170:173], v[42:45]
	v_mfma_f32_16x16x32_bf16 v[30:33], v[66:69], v[178:181], v[30:33]
	v_mfma_f32_16x16x32_bf16 v[26:29], v[74:77], v[178:181], v[26:29]
	v_mfma_f32_16x16x32_bf16 v[14:17], v[66:69], v[186:189], v[14:17]
	v_mfma_f32_16x16x32_bf16 v[10:13], v[74:77], v[186:189], v[10:13]
	v_mfma_f32_16x16x32_bf16 v[62:65], v[70:73], v[166:169], v[62:65]
	v_mfma_f32_16x16x32_bf16 v[58:61], v[78:81], v[166:169], v[58:61]
	v_mfma_f32_16x16x32_bf16 v[46:49], v[70:73], v[174:177], v[46:49]
	v_mfma_f32_16x16x32_bf16 v[42:45], v[78:81], v[174:177], v[42:45]
	v_mfma_f32_16x16x32_bf16 v[30:33], v[70:73], v[182:185], v[30:33]
	v_mfma_f32_16x16x32_bf16 v[26:29], v[78:81], v[182:185], v[26:29]
	v_mfma_f32_16x16x32_bf16 v[14:17], v[70:73], v[190:193], v[14:17]
	v_mfma_f32_16x16x32_bf16 v[10:13], v[78:81], v[190:193], v[10:13]
	v_mfma_f32_16x16x32_bf16 v[54:57], v[82:85], v[162:165], v[54:57]
	v_mfma_f32_16x16x32_bf16 v[50:53], v[90:93], v[162:165], v[50:53]
	v_mfma_f32_16x16x32_bf16 v[38:41], v[82:85], v[170:173], v[38:41]
	v_mfma_f32_16x16x32_bf16 v[34:37], v[90:93], v[170:173], v[34:37]
	v_mfma_f32_16x16x32_bf16 v[22:25], v[82:85], v[178:181], v[22:25]
	v_mfma_f32_16x16x32_bf16 v[18:21], v[90:93], v[178:181], v[18:21]
	v_mfma_f32_16x16x32_bf16 v[6:9], v[82:85], v[186:189], v[6:9]
	v_mfma_f32_16x16x32_bf16 v[2:5], v[90:93], v[186:189], v[2:5]
	v_mfma_f32_16x16x32_bf16 v[54:57], v[86:89], v[166:169], v[54:57]
	v_mfma_f32_16x16x32_bf16 v[50:53], v[94:97], v[166:169], v[50:53]
	v_mfma_f32_16x16x32_bf16 v[38:41], v[86:89], v[174:177], v[38:41]
	v_mfma_f32_16x16x32_bf16 v[34:37], v[94:97], v[174:177], v[34:37]
	v_mfma_f32_16x16x32_bf16 v[22:25], v[86:89], v[182:185], v[22:25]
	v_mfma_f32_16x16x32_bf16 v[18:21], v[94:97], v[182:185], v[18:21]
	v_mfma_f32_16x16x32_bf16 v[6:9], v[86:89], v[190:193], v[6:9]
	v_mfma_f32_16x16x32_bf16 v[2:5], v[94:97], v[190:193], v[2:5]
	s_setprio 0
	s_barrier
	s_add_i32 s63, 0, 0x18000
	s_add_i32 s66, 0, 0x1c000
	v_add_u32_e32 v78, s63, v251
	v_add_u32_e32 v94, s66, v251
	ds_read_b128 v[66:69], v78
	ds_read_b128 v[70:73], v78 offset:1024
	ds_read_b128 v[74:77], v78 offset:2048
	ds_read_b128 v[78:81], v78 offset:3072
	ds_read_b128 v[82:85], v94
	ds_read_b128 v[86:89], v94 offset:1024
	ds_read_b128 v[90:93], v94 offset:2048
	ds_read_b128 v[94:97], v94 offset:3072
	s_add_u32 s34, s46, 0x80000
	s_addc_u32 s35, s47, 0
	s_mov_b32 m0, s53
	ds_read_b128 v[162:165], v244 offset:32768
	ds_read_b128 v[166:169], v244 offset:33792
	ds_read_b128 v[170:173], v244 offset:34816
	ds_read_b128 v[174:177], v244 offset:35840
	ds_read_b128 v[178:181], v244 offset:36864
	ds_read_b128 v[182:185], v244 offset:37888
	ds_read_b128 v[186:189], v244 offset:38912
	ds_read_b128 v[190:193], v244 offset:39936
	global_load_lds_dwordx4 v210, s[34:35]
	s_mov_b32 m0, s54
	s_nop 0
	global_load_lds_dwordx4 v216, s[34:35]
	s_waitcnt vmcnt(8) lgkmcnt(0)
	s_barrier
	s_setprio 1
	v_mfma_f32_16x16x32_bf16 v[158:161], v[66:69], v[162:165], v[158:161]
	v_mfma_f32_16x16x32_bf16 v[154:157], v[74:77], v[162:165], v[154:157]
	v_mfma_f32_16x16x32_bf16 v[142:145], v[66:69], v[170:173], v[142:145]
	v_mfma_f32_16x16x32_bf16 v[138:141], v[74:77], v[170:173], v[138:141]
	v_mfma_f32_16x16x32_bf16 v[126:129], v[66:69], v[178:181], v[126:129]
	v_mfma_f32_16x16x32_bf16 v[122:125], v[74:77], v[178:181], v[122:125]
	v_mfma_f32_16x16x32_bf16 v[110:113], v[66:69], v[186:189], v[110:113]
	v_mfma_f32_16x16x32_bf16 v[106:109], v[74:77], v[186:189], v[106:109]
	v_mfma_f32_16x16x32_bf16 v[158:161], v[70:73], v[166:169], v[158:161]
	v_mfma_f32_16x16x32_bf16 v[154:157], v[78:81], v[166:169], v[154:157]
	v_mfma_f32_16x16x32_bf16 v[142:145], v[70:73], v[174:177], v[142:145]
	v_mfma_f32_16x16x32_bf16 v[138:141], v[78:81], v[174:177], v[138:141]
	v_mfma_f32_16x16x32_bf16 v[126:129], v[70:73], v[182:185], v[126:129]
	v_mfma_f32_16x16x32_bf16 v[122:125], v[78:81], v[182:185], v[122:125]
	v_mfma_f32_16x16x32_bf16 v[110:113], v[70:73], v[190:193], v[110:113]
	v_mfma_f32_16x16x32_bf16 v[106:109], v[78:81], v[190:193], v[106:109]
	v_mfma_f32_16x16x32_bf16 v[150:153], v[82:85], v[162:165], v[150:153]
	v_mfma_f32_16x16x32_bf16 v[146:149], v[90:93], v[162:165], v[146:149]
	v_mfma_f32_16x16x32_bf16 v[134:137], v[82:85], v[170:173], v[134:137]
	v_mfma_f32_16x16x32_bf16 v[130:133], v[90:93], v[170:173], v[130:133]
	v_mfma_f32_16x16x32_bf16 v[118:121], v[82:85], v[178:181], v[118:121]
	v_mfma_f32_16x16x32_bf16 v[114:117], v[90:93], v[178:181], v[114:117]
	v_mfma_f32_16x16x32_bf16 v[102:105], v[82:85], v[186:189], v[102:105]
	v_mfma_f32_16x16x32_bf16 v[98:101], v[90:93], v[186:189], v[98:101]
	v_mfma_f32_16x16x32_bf16 v[150:153], v[86:89], v[166:169], v[150:153]
	v_mfma_f32_16x16x32_bf16 v[146:149], v[94:97], v[166:169], v[146:149]
	v_mfma_f32_16x16x32_bf16 v[134:137], v[86:89], v[174:177], v[134:137]
	v_mfma_f32_16x16x32_bf16 v[130:133], v[94:97], v[174:177], v[130:133]
	v_mfma_f32_16x16x32_bf16 v[118:121], v[86:89], v[182:185], v[118:121]
	v_mfma_f32_16x16x32_bf16 v[114:117], v[94:97], v[182:185], v[114:117]
	v_mfma_f32_16x16x32_bf16 v[102:105], v[86:89], v[190:193], v[102:105]
	v_mfma_f32_16x16x32_bf16 v[98:101], v[94:97], v[190:193], v[98:101]
	s_setprio 0
	s_barrier
	s_add_i32 s34, s63, s44
	v_lshl_add_u64 v[194:195], v[194:195], 0, s[64:65]
	s_mov_b32 m0, s34
	ds_read_b128 v[162:165], v244 offset:49152
	ds_read_b128 v[166:169], v244 offset:50176
	ds_read_b128 v[170:173], v244 offset:51200
	ds_read_b128 v[174:177], v244 offset:52224
	ds_read_b128 v[178:181], v244 offset:53248
	ds_read_b128 v[182:185], v244 offset:54272
	ds_read_b128 v[186:189], v244 offset:55296
	ds_read_b128 v[190:193], v244 offset:56320
	global_load_lds_dwordx4 v[194:195], off
	s_add_i32 m0, s34, 0x2000
	s_add_u32 s34, s42, 0x80080
	v_lshl_add_u64 v[194:195], v[196:197], 0, s[64:65]
	s_addc_u32 s35, s43, 0
	s_add_i32 s42, s66, s44
	global_load_lds_dwordx4 v[194:195], off
	s_mov_b32 m0, s42
	s_nop 0
	global_load_lds_dwordx4 v210, s[34:35]
	s_add_i32 m0, s42, 0x2000
	s_nop 0
	global_load_lds_dwordx4 v216, s[34:35]
	v_lshl_add_u64 v[194:195], v[198:199], 0, s[64:65]
	s_mov_b32 m0, s55
	s_nop 0
	global_load_lds_dwordx4 v[194:195], off
	v_lshl_add_u64 v[194:195], v[200:201], 0, s[64:65]
	s_mov_b32 m0, s56
	s_nop 0
	global_load_lds_dwordx4 v[194:195], off
	s_waitcnt vmcnt(8) lgkmcnt(0)
	s_barrier
	s_setprio 1
	v_mfma_f32_16x16x32_bf16 v[62:65], v[66:69], v[162:165], v[62:65]
	v_mfma_f32_16x16x32_bf16 v[58:61], v[74:77], v[162:165], v[58:61]
	v_mfma_f32_16x16x32_bf16 v[46:49], v[66:69], v[170:173], v[46:49]
	v_mfma_f32_16x16x32_bf16 v[42:45], v[74:77], v[170:173], v[42:45]
	v_mfma_f32_16x16x32_bf16 v[30:33], v[66:69], v[178:181], v[30:33]
	v_mfma_f32_16x16x32_bf16 v[26:29], v[74:77], v[178:181], v[26:29]
	v_mfma_f32_16x16x32_bf16 v[14:17], v[66:69], v[186:189], v[14:17]
	v_mfma_f32_16x16x32_bf16 v[10:13], v[74:77], v[186:189], v[10:13]
	v_mfma_f32_16x16x32_bf16 v[62:65], v[70:73], v[166:169], v[62:65]
	v_mfma_f32_16x16x32_bf16 v[58:61], v[78:81], v[166:169], v[58:61]
	v_mfma_f32_16x16x32_bf16 v[46:49], v[70:73], v[174:177], v[46:49]
	v_mfma_f32_16x16x32_bf16 v[42:45], v[78:81], v[174:177], v[42:45]
	v_mfma_f32_16x16x32_bf16 v[30:33], v[70:73], v[182:185], v[30:33]
	v_mfma_f32_16x16x32_bf16 v[26:29], v[78:81], v[182:185], v[26:29]
	v_mfma_f32_16x16x32_bf16 v[14:17], v[70:73], v[190:193], v[14:17]
	v_mfma_f32_16x16x32_bf16 v[10:13], v[78:81], v[190:193], v[10:13]
	v_mfma_f32_16x16x32_bf16 v[54:57], v[82:85], v[162:165], v[54:57]
	v_mfma_f32_16x16x32_bf16 v[50:53], v[90:93], v[162:165], v[50:53]
	v_mfma_f32_16x16x32_bf16 v[38:41], v[82:85], v[170:173], v[38:41]
	v_mfma_f32_16x16x32_bf16 v[34:37], v[90:93], v[170:173], v[34:37]
	v_mfma_f32_16x16x32_bf16 v[22:25], v[82:85], v[178:181], v[22:25]
	v_mfma_f32_16x16x32_bf16 v[18:21], v[90:93], v[178:181], v[18:21]
	v_mfma_f32_16x16x32_bf16 v[6:9], v[82:85], v[186:189], v[6:9]
	v_mfma_f32_16x16x32_bf16 v[2:5], v[90:93], v[186:189], v[2:5]
	v_mfma_f32_16x16x32_bf16 v[54:57], v[86:89], v[166:169], v[54:57]
	v_mfma_f32_16x16x32_bf16 v[50:53], v[94:97], v[166:169], v[50:53]
	v_mfma_f32_16x16x32_bf16 v[38:41], v[86:89], v[174:177], v[38:41]
	v_mfma_f32_16x16x32_bf16 v[34:37], v[94:97], v[174:177], v[34:37]
	v_mfma_f32_16x16x32_bf16 v[22:25], v[86:89], v[182:185], v[22:25]
	v_mfma_f32_16x16x32_bf16 v[18:21], v[94:97], v[182:185], v[18:21]
	v_mfma_f32_16x16x32_bf16 v[6:9], v[86:89], v[190:193], v[6:9]
	v_mfma_f32_16x16x32_bf16 v[2:5], v[94:97], v[190:193], v[2:5]
	s_setprio 0
	s_barrier
	s_add_i32 s62, s62, 2
	s_add_u32 s60, s60, 0x100
	s_addc_u32 s61, s61, 0
	s_cmp_gt_u32 s62, 29
	s_mov_b64 s[34:35], s[10:11]
	s_cbranch_scc0 .LBB0_956
	s_and_b64 vcc, exec, s[26:27]
	s_cbranch_vccz .LBB0_959
	s_barrier

.LBB0_1091:
	s_add_u32 s30, s26, 0xfff80080
	s_addc_u32 s31, s27, -1
	s_add_i32 s51, 0, 0x10000
	s_cmp_eq_u32 s50, 28
	s_cselect_b32 s35, s2, s31
	s_cselect_b32 s34, s3, s30
	s_cselect_b32 s31, s19, s49
	s_cselect_b32 s30, s21, s48
	s_add_i32 s54, 0, 0x14000
	v_add_u32_e32 v142, s51, v181
	v_add_u32_e32 v158, s54, v181
	ds_read_b128 v[130:133], v142
	ds_read_b128 v[134:137], v142 offset:1024
	ds_read_b128 v[138:141], v142 offset:2048
	ds_read_b128 v[142:145], v142 offset:3072
	ds_read_b128 v[146:149], v158
	ds_read_b128 v[150:153], v158 offset:1024
	ds_read_b128 v[154:157], v158 offset:2048
	ds_read_b128 v[158:161], v158 offset:3072
	s_add_i32 m0, s41, 0xc000
	ds_read_b128 v[176:179], v195
	ds_read_b128 v[182:185], v195 offset:1024
	ds_read_b128 v[190:193], v195 offset:2048
	ds_read_b128 v[196:199], v195 offset:3072
	ds_read_b128 v[200:203], v195 offset:4096
	ds_read_b128 v[204:207], v195 offset:5120
	ds_read_b128 v[216:219], v195 offset:6144
	ds_read_b128 v[220:223], v195 offset:7168
	global_load_lds_dwordx4 v168, s[26:27]
	s_add_i32 m0, s41, 0xe000
	s_nop 0
	global_load_lds_dwordx4 v170, s[26:27]
	s_waitcnt vmcnt(8) lgkmcnt(0)
	s_barrier
	s_setprio 1
	v_mfma_f32_16x16x32_bf16 v[126:129], v[130:133], v[176:179], v[126:129]
	v_mfma_f32_16x16x32_bf16 v[122:125], v[138:141], v[176:179], v[122:125]
	v_mfma_f32_16x16x32_bf16 v[110:113], v[130:133], v[190:193], v[110:113]
	v_mfma_f32_16x16x32_bf16 v[106:109], v[138:141], v[190:193], v[106:109]
	v_mfma_f32_16x16x32_bf16 v[94:97], v[130:133], v[200:203], v[94:97]
	v_mfma_f32_16x16x32_bf16 v[90:93], v[138:141], v[200:203], v[90:93]
	v_mfma_f32_16x16x32_bf16 v[78:81], v[130:133], v[216:219], v[78:81]
	v_mfma_f32_16x16x32_bf16 v[74:77], v[138:141], v[216:219], v[74:77]
	v_mfma_f32_16x16x32_bf16 v[126:129], v[134:137], v[182:185], v[126:129]
	v_mfma_f32_16x16x32_bf16 v[122:125], v[142:145], v[182:185], v[122:125]
	v_mfma_f32_16x16x32_bf16 v[110:113], v[134:137], v[196:199], v[110:113]
	v_mfma_f32_16x16x32_bf16 v[106:109], v[142:145], v[196:199], v[106:109]
	v_mfma_f32_16x16x32_bf16 v[94:97], v[134:137], v[204:207], v[94:97]
	v_mfma_f32_16x16x32_bf16 v[90:93], v[142:145], v[204:207], v[90:93]
	v_mfma_f32_16x16x32_bf16 v[78:81], v[134:137], v[220:223], v[78:81]
	v_mfma_f32_16x16x32_bf16 v[74:77], v[142:145], v[220:223], v[74:77]
	v_mfma_f32_16x16x32_bf16 v[118:121], v[146:149], v[176:179], v[118:121]
	v_mfma_f32_16x16x32_bf16 v[114:117], v[154:157], v[176:179], v[114:117]
	v_mfma_f32_16x16x32_bf16 v[102:105], v[146:149], v[190:193], v[102:105]
	v_mfma_f32_16x16x32_bf16 v[98:101], v[154:157], v[190:193], v[98:101]
	v_mfma_f32_16x16x32_bf16 v[86:89], v[146:149], v[200:203], v[86:89]
	v_mfma_f32_16x16x32_bf16 v[82:85], v[154:157], v[200:203], v[82:85]
	v_mfma_f32_16x16x32_bf16 v[70:73], v[146:149], v[216:219], v[70:73]
	v_mfma_f32_16x16x32_bf16 v[66:69], v[154:157], v[216:219], v[66:69]
	v_mfma_f32_16x16x32_bf16 v[118:121], v[150:153], v[182:185], v[118:121]
	v_mfma_f32_16x16x32_bf16 v[114:117], v[158:161], v[182:185], v[114:117]
	v_mfma_f32_16x16x32_bf16 v[102:105], v[150:153], v[196:199], v[102:105]
	v_mfma_f32_16x16x32_bf16 v[98:101], v[158:161], v[196:199], v[98:101]
	v_mfma_f32_16x16x32_bf16 v[86:89], v[150:153], v[204:207], v[86:89]
	v_mfma_f32_16x16x32_bf16 v[82:85], v[158:161], v[204:207], v[82:85]
	v_mfma_f32_16x16x32_bf16 v[70:73], v[150:153], v[220:223], v[70:73]
	v_mfma_f32_16x16x32_bf16 v[66:69], v[158:161], v[220:223], v[66:69]
	s_setprio 0
	s_barrier
	s_add_i32 s51, s51, s40
	v_lshl_add_u64 v[172:173], s[30:31], 0, v[210:211]
	s_mov_b32 m0, s51
	ds_read_b128 v[176:179], v195 offset:16384
	ds_read_b128 v[182:185], v195 offset:17408
	ds_read_b128 v[190:193], v195 offset:18432
	ds_read_b128 v[196:199], v195 offset:19456
	ds_read_b128 v[200:203], v195 offset:20480
	ds_read_b128 v[204:207], v195 offset:21504
	ds_read_b128 v[216:219], v195 offset:22528
	ds_read_b128 v[220:223], v195 offset:23552
	global_load_lds_dwordx4 v[172:173], off
	s_add_i32 m0, s51, 0x2000
	s_add_u32 s52, s30, 0x80000
	v_lshl_add_u64 v[186:187], s[30:31], 0, v[162:163]
	s_addc_u32 s53, s31, 0
	s_add_i32 s51, s54, s40
	global_load_lds_dwordx4 v[186:187], off
	s_mov_b32 m0, s51
	v_lshl_add_u64 v[212:213], s[34:35], 0, v[164:165]
	global_load_lds_dwordx4 v210, s[52:53]
	s_add_i32 m0, s51, 0x2000
	s_nop 0
	global_load_lds_dwordx4 v162, s[52:53]
	v_lshl_add_u64 v[208:209], s[34:35], 0, v[166:167]
	s_mov_b32 m0, s41
	s_nop 0
	global_load_lds_dwordx4 v[208:209], off
	s_mov_b32 m0, s42
	s_nop 0
	global_load_lds_dwordx4 v[212:213], off
	s_waitcnt vmcnt(8) lgkmcnt(0)
	s_barrier
	s_setprio 1
	v_mfma_f32_16x16x32_bf16 v[62:65], v[130:133], v[176:179], v[62:65]
	v_mfma_f32_16x16x32_bf16 v[58:61], v[138:141], v[176:179], v[58:61]
	v_mfma_f32_16x16x32_bf16 v[46:49], v[130:133], v[190:193], v[46:49]
	v_mfma_f32_16x16x32_bf16 v[42:45], v[138:141], v[190:193], v[42:45]
	v_mfma_f32_16x16x32_bf16 v[30:33], v[130:133], v[200:203], v[30:33]
	v_mfma_f32_16x16x32_bf16 v[26:29], v[138:141], v[200:203], v[26:29]
	v_mfma_f32_16x16x32_bf16 v[14:17], v[130:133], v[216:219], v[14:17]
	v_mfma_f32_16x16x32_bf16 v[10:13], v[138:141], v[216:219], v[10:13]
	v_mfma_f32_16x16x32_bf16 v[62:65], v[134:137], v[182:185], v[62:65]
	v_mfma_f32_16x16x32_bf16 v[58:61], v[142:145], v[182:185], v[58:61]
	v_mfma_f32_16x16x32_bf16 v[46:49], v[134:137], v[196:199], v[46:49]
	v_mfma_f32_16x16x32_bf16 v[42:45], v[142:145], v[196:199], v[42:45]
	v_mfma_f32_16x16x32_bf16 v[30:33], v[134:137], v[204:207], v[30:33]
	v_mfma_f32_16x16x32_bf16 v[26:29], v[142:145], v[204:207], v[26:29]
	v_mfma_f32_16x16x32_bf16 v[14:17], v[134:137], v[220:223], v[14:17]
	v_mfma_f32_16x16x32_bf16 v[10:13], v[142:145], v[220:223], v[10:13]
	v_mfma_f32_16x16x32_bf16 v[54:57], v[146:149], v[176:179], v[54:57]
	v_mfma_f32_16x16x32_bf16 v[50:53], v[154:157], v[176:179], v[50:53]
	v_mfma_f32_16x16x32_bf16 v[38:41], v[146:149], v[190:193], v[38:41]
	v_mfma_f32_16x16x32_bf16 v[34:37], v[154:157], v[190:193], v[34:37]
	v_mfma_f32_16x16x32_bf16 v[22:25], v[146:149], v[200:203], v[22:25]
	v_mfma_f32_16x16x32_bf16 v[18:21], v[154:157], v[200:203], v[18:21]
	v_mfma_f32_16x16x32_bf16 v[6:9], v[146:149], v[216:219], v[6:9]
	v_mfma_f32_16x16x32_bf16 v[2:5], v[154:157], v[216:219], v[2:5]
	v_mfma_f32_16x16x32_bf16 v[54:57], v[150:153], v[182:185], v[54:57]
	v_mfma_f32_16x16x32_bf16 v[50:53], v[158:161], v[182:185], v[50:53]
	v_mfma_f32_16x16x32_bf16 v[38:41], v[150:153], v[196:199], v[38:41]
	v_mfma_f32_16x16x32_bf16 v[34:37], v[158:161], v[196:199], v[34:37]
	v_mfma_f32_16x16x32_bf16 v[22:25], v[150:153], v[204:207], v[22:25]
	v_mfma_f32_16x16x32_bf16 v[18:21], v[158:161], v[204:207], v[18:21]
	v_mfma_f32_16x16x32_bf16 v[6:9], v[150:153], v[220:223], v[6:9]
	v_mfma_f32_16x16x32_bf16 v[2:5], v[158:161], v[220:223], v[2:5]
	s_setprio 0
	s_barrier
	s_add_i32 s51, 0, 0x18000
	s_add_i32 s52, 0, 0x1c000
	v_add_u32_e32 v142, s51, v181
	v_add_u32_e32 v158, s52, v181
	ds_read_b128 v[130:133], v142
	ds_read_b128 v[134:137], v142 offset:1024
	ds_read_b128 v[138:141], v142 offset:2048
	ds_read_b128 v[142:145], v142 offset:3072
	ds_read_b128 v[146:149], v158
	ds_read_b128 v[150:153], v158 offset:1024
	ds_read_b128 v[154:157], v158 offset:2048
	ds_read_b128 v[158:161], v158 offset:3072
	s_add_u32 s34, s34, 0x80000
	s_addc_u32 s35, s35, 0
	s_mov_b32 m0, s43
	ds_read_b128 v[176:179], v195 offset:32768
	ds_read_b128 v[182:185], v195 offset:33792
	ds_read_b128 v[190:193], v195 offset:34816
	ds_read_b128 v[196:199], v195 offset:35840
	ds_read_b128 v[200:203], v195 offset:36864
	ds_read_b128 v[204:207], v195 offset:37888
	ds_read_b128 v[216:219], v195 offset:38912
	ds_read_b128 v[220:223], v195 offset:39936
	global_load_lds_dwordx4 v166, s[34:35]
	s_mov_b32 m0, s44
	s_nop 0
	global_load_lds_dwordx4 v164, s[34:35]
	s_waitcnt vmcnt(8) lgkmcnt(0)
	s_barrier
	s_setprio 1
	v_mfma_f32_16x16x32_bf16 v[126:129], v[130:133], v[176:179], v[126:129]
	v_mfma_f32_16x16x32_bf16 v[122:125], v[138:141], v[176:179], v[122:125]
	v_mfma_f32_16x16x32_bf16 v[110:113], v[130:133], v[190:193], v[110:113]
	v_mfma_f32_16x16x32_bf16 v[106:109], v[138:141], v[190:193], v[106:109]
	v_mfma_f32_16x16x32_bf16 v[94:97], v[130:133], v[200:203], v[94:97]
	v_mfma_f32_16x16x32_bf16 v[90:93], v[138:141], v[200:203], v[90:93]
	v_mfma_f32_16x16x32_bf16 v[78:81], v[130:133], v[216:219], v[78:81]
	v_mfma_f32_16x16x32_bf16 v[74:77], v[138:141], v[216:219], v[74:77]
	v_mfma_f32_16x16x32_bf16 v[126:129], v[134:137], v[182:185], v[126:129]
	v_mfma_f32_16x16x32_bf16 v[122:125], v[142:145], v[182:185], v[122:125]
	v_mfma_f32_16x16x32_bf16 v[110:113], v[134:137], v[196:199], v[110:113]
	v_mfma_f32_16x16x32_bf16 v[106:109], v[142:145], v[196:199], v[106:109]
	v_mfma_f32_16x16x32_bf16 v[94:97], v[134:137], v[204:207], v[94:97]
	v_mfma_f32_16x16x32_bf16 v[90:93], v[142:145], v[204:207], v[90:93]
	v_mfma_f32_16x16x32_bf16 v[78:81], v[134:137], v[220:223], v[78:81]
	v_mfma_f32_16x16x32_bf16 v[74:77], v[142:145], v[220:223], v[74:77]
	v_mfma_f32_16x16x32_bf16 v[118:121], v[146:149], v[176:179], v[118:121]
	v_mfma_f32_16x16x32_bf16 v[114:117], v[154:157], v[176:179], v[114:117]
	v_mfma_f32_16x16x32_bf16 v[102:105], v[146:149], v[190:193], v[102:105]
	v_mfma_f32_16x16x32_bf16 v[98:101], v[154:157], v[190:193], v[98:101]
	v_mfma_f32_16x16x32_bf16 v[86:89], v[146:149], v[200:203], v[86:89]
	v_mfma_f32_16x16x32_bf16 v[82:85], v[154:157], v[200:203], v[82:85]
	v_mfma_f32_16x16x32_bf16 v[70:73], v[146:149], v[216:219], v[70:73]
	v_mfma_f32_16x16x32_bf16 v[66:69], v[154:157], v[216:219], v[66:69]
	v_mfma_f32_16x16x32_bf16 v[118:121], v[150:153], v[182:185], v[118:121]
	v_mfma_f32_16x16x32_bf16 v[114:117], v[158:161], v[182:185], v[114:117]
	v_mfma_f32_16x16x32_bf16 v[102:105], v[150:153], v[196:199], v[102:105]
	v_mfma_f32_16x16x32_bf16 v[98:101], v[158:161], v[196:199], v[98:101]
	v_mfma_f32_16x16x32_bf16 v[86:89], v[150:153], v[204:207], v[86:89]
	v_mfma_f32_16x16x32_bf16 v[82:85], v[158:161], v[204:207], v[82:85]
	v_mfma_f32_16x16x32_bf16 v[70:73], v[150:153], v[220:223], v[70:73]
	v_mfma_f32_16x16x32_bf16 v[66:69], v[158:161], v[220:223], v[66:69]
	s_setprio 0
	s_barrier
	s_add_i32 s34, s51, s40
	v_lshl_add_u64 v[172:173], v[172:173], 0, s[64:65]
	s_mov_b32 m0, s34
	ds_read_b128 v[176:179], v195 offset:49152
	ds_read_b128 v[182:185], v195 offset:50176
	ds_read_b128 v[190:193], v195 offset:51200
	ds_read_b128 v[196:199], v195 offset:52224
	ds_read_b128 v[200:203], v195 offset:53248
	ds_read_b128 v[204:207], v195 offset:54272
	ds_read_b128 v[216:219], v195 offset:55296
	ds_read_b128 v[220:223], v195 offset:56320
	global_load_lds_dwordx4 v[172:173], off
	s_add_i32 m0, s34, 0x2000
	s_add_u32 s30, s30, 0x80080
	v_lshl_add_u64 v[172:173], v[186:187], 0, s[64:65]
	s_addc_u32 s31, s31, 0
	s_add_i32 s34, s52, s40
	global_load_lds_dwordx4 v[172:173], off
	s_mov_b32 m0, s34
	s_nop 0
	global_load_lds_dwordx4 v210, s[30:31]
	s_add_i32 m0, s34, 0x2000
	s_nop 0
	global_load_lds_dwordx4 v162, s[30:31]
	v_lshl_add_u64 v[172:173], v[208:209], 0, s[64:65]
	s_mov_b32 m0, s45
	s_nop 0
	global_load_lds_dwordx4 v[172:173], off
	v_lshl_add_u64 v[172:173], v[212:213], 0, s[64:65]
	s_mov_b32 m0, s46
	s_nop 0
	global_load_lds_dwordx4 v[172:173], off
	s_waitcnt vmcnt(8) lgkmcnt(0)
	s_barrier
	s_setprio 1
	v_mfma_f32_16x16x32_bf16 v[62:65], v[130:133], v[176:179], v[62:65]
	v_mfma_f32_16x16x32_bf16 v[58:61], v[138:141], v[176:179], v[58:61]
	v_mfma_f32_16x16x32_bf16 v[46:49], v[130:133], v[190:193], v[46:49]
	v_mfma_f32_16x16x32_bf16 v[42:45], v[138:141], v[190:193], v[42:45]
	v_mfma_f32_16x16x32_bf16 v[30:33], v[130:133], v[200:203], v[30:33]
	v_mfma_f32_16x16x32_bf16 v[26:29], v[138:141], v[200:203], v[26:29]
	v_mfma_f32_16x16x32_bf16 v[14:17], v[130:133], v[216:219], v[14:17]
	v_mfma_f32_16x16x32_bf16 v[10:13], v[138:141], v[216:219], v[10:13]
	v_mfma_f32_16x16x32_bf16 v[62:65], v[134:137], v[182:185], v[62:65]
	v_mfma_f32_16x16x32_bf16 v[58:61], v[142:145], v[182:185], v[58:61]
	v_mfma_f32_16x16x32_bf16 v[46:49], v[134:137], v[196:199], v[46:49]
	v_mfma_f32_16x16x32_bf16 v[42:45], v[142:145], v[196:199], v[42:45]
	v_mfma_f32_16x16x32_bf16 v[30:33], v[134:137], v[204:207], v[30:33]
	v_mfma_f32_16x16x32_bf16 v[26:29], v[142:145], v[204:207], v[26:29]
	v_mfma_f32_16x16x32_bf16 v[14:17], v[134:137], v[220:223], v[14:17]
	v_mfma_f32_16x16x32_bf16 v[10:13], v[142:145], v[220:223], v[10:13]
	v_mfma_f32_16x16x32_bf16 v[54:57], v[146:149], v[176:179], v[54:57]
	v_mfma_f32_16x16x32_bf16 v[50:53], v[154:157], v[176:179], v[50:53]
	v_mfma_f32_16x16x32_bf16 v[38:41], v[146:149], v[190:193], v[38:41]
	v_mfma_f32_16x16x32_bf16 v[34:37], v[154:157], v[190:193], v[34:37]
	v_mfma_f32_16x16x32_bf16 v[22:25], v[146:149], v[200:203], v[22:25]
	v_mfma_f32_16x16x32_bf16 v[18:21], v[154:157], v[200:203], v[18:21]
	v_mfma_f32_16x16x32_bf16 v[6:9], v[146:149], v[216:219], v[6:9]
	v_mfma_f32_16x16x32_bf16 v[2:5], v[154:157], v[216:219], v[2:5]
	v_mfma_f32_16x16x32_bf16 v[54:57], v[150:153], v[182:185], v[54:57]
	v_mfma_f32_16x16x32_bf16 v[50:53], v[158:161], v[182:185], v[50:53]
	v_mfma_f32_16x16x32_bf16 v[38:41], v[150:153], v[196:199], v[38:41]
	v_mfma_f32_16x16x32_bf16 v[34:37], v[158:161], v[196:199], v[34:37]
	v_mfma_f32_16x16x32_bf16 v[22:25], v[150:153], v[204:207], v[22:25]
	v_mfma_f32_16x16x32_bf16 v[18:21], v[158:161], v[204:207], v[18:21]
	v_mfma_f32_16x16x32_bf16 v[6:9], v[150:153], v[220:223], v[6:9]
	v_mfma_f32_16x16x32_bf16 v[2:5], v[158:161], v[220:223], v[2:5]
	s_setprio 0
	s_barrier
	s_add_i32 s50, s50, 2
	s_add_u32 s26, s26, 0x100
	s_addc_u32 s27, s27, 0
	s_add_u32 s48, s48, 0x100
	s_addc_u32 s49, s49, 0
	s_cmp_gt_u32 s50, 29
	s_cbranch_scc0 .LBB0_1091
	v_readlane_b32 s50, v254, 38
	s_and_b64 vcc, exec, s[16:17]
	v_readlane_b32 s51, v254, 39
	s_cbranch_vccz .LBB0_1094
	s_barrier

.LBB0_1180:
	s_add_u32 s36, s34, 0x100
	s_addc_u32 s37, s35, 0
	s_add_i32 s57, 0, 0x10000
	s_cmpk_eq_i32 s56, 0x7c
	s_cselect_b32 s41, s2, s37
	s_cselect_b32 s40, s3, s36
	s_cselect_b32 s39, s23, s55
	s_cselect_b32 s38, s25, s54
	s_add_i32 s58, 0, 0x14000
	v_add_u32_e32 v78, s57, v233
	v_add_u32_e32 v98, s58, v233
	ds_read_b128 v[66:69], v78
	ds_read_b128 v[70:73], v78 offset:1024
	ds_read_b128 v[74:77], v78 offset:2048
	ds_read_b128 v[78:81], v78 offset:3072
	ds_read_b128 v[82:85], v98
	ds_read_b128 v[86:89], v98 offset:1024
	ds_read_b128 v[94:97], v98 offset:2048
	ds_read_b128 v[98:101], v98 offset:3072
	v_lshl_add_u64 v[200:201], s[34:35], 0, v[196:197]
	s_add_i32 m0, s47, 0xc000
	ds_read_b128 v[162:165], v235
	ds_read_b128 v[166:169], v235 offset:1024
	ds_read_b128 v[170:173], v235 offset:2048
	ds_read_b128 v[174:177], v235 offset:3072
	ds_read_b128 v[178:181], v235 offset:4096
	ds_read_b128 v[182:185], v235 offset:5120
	ds_read_b128 v[186:189], v235 offset:6144
	ds_read_b128 v[190:193], v235 offset:7168
	global_load_lds_dwordx4 v[200:201], off
	v_lshl_add_u64 v[200:201], s[34:35], 0, v[198:199]
	s_add_i32 m0, s47, 0xe000
	s_nop 0
	global_load_lds_dwordx4 v[200:201], off
	s_waitcnt vmcnt(8) lgkmcnt(0)
	s_barrier
	s_setprio 1
	v_mfma_f32_16x16x32_bf16 v[158:161], v[66:69], v[162:165], v[158:161]
	v_mfma_f32_16x16x32_bf16 v[154:157], v[74:77], v[162:165], v[154:157]
	v_mfma_f32_16x16x32_bf16 v[142:145], v[66:69], v[170:173], v[142:145]
	v_mfma_f32_16x16x32_bf16 v[138:141], v[74:77], v[170:173], v[138:141]
	v_mfma_f32_16x16x32_bf16 v[126:129], v[66:69], v[178:181], v[126:129]
	v_mfma_f32_16x16x32_bf16 v[122:125], v[74:77], v[178:181], v[122:125]
	v_mfma_f32_16x16x32_bf16 v[110:113], v[66:69], v[186:189], v[110:113]
	v_mfma_f32_16x16x32_bf16 v[106:109], v[74:77], v[186:189], v[106:109]
	v_mfma_f32_16x16x32_bf16 v[158:161], v[70:73], v[166:169], v[158:161]
	v_mfma_f32_16x16x32_bf16 v[154:157], v[78:81], v[166:169], v[154:157]
	v_mfma_f32_16x16x32_bf16 v[142:145], v[70:73], v[174:177], v[142:145]
	v_mfma_f32_16x16x32_bf16 v[138:141], v[78:81], v[174:177], v[138:141]
	v_mfma_f32_16x16x32_bf16 v[126:129], v[70:73], v[182:185], v[126:129]
	v_mfma_f32_16x16x32_bf16 v[122:125], v[78:81], v[182:185], v[122:125]
	v_mfma_f32_16x16x32_bf16 v[110:113], v[70:73], v[190:193], v[110:113]
	v_mfma_f32_16x16x32_bf16 v[106:109], v[78:81], v[190:193], v[106:109]
	v_mfma_f32_16x16x32_bf16 v[150:153], v[82:85], v[162:165], v[150:153]
	v_mfma_f32_16x16x32_bf16 v[146:149], v[94:97], v[162:165], v[146:149]
	v_mfma_f32_16x16x32_bf16 v[134:137], v[82:85], v[170:173], v[134:137]
	v_mfma_f32_16x16x32_bf16 v[130:133], v[94:97], v[170:173], v[130:133]
	v_mfma_f32_16x16x32_bf16 v[118:121], v[82:85], v[178:181], v[118:121]
	v_mfma_f32_16x16x32_bf16 v[114:117], v[94:97], v[178:181], v[114:117]
	v_mfma_f32_16x16x32_bf16 v[102:105], v[82:85], v[186:189], v[102:105]
	v_mfma_f32_16x16x32_bf16 v[90:93], v[94:97], v[186:189], v[90:93]
	v_mfma_f32_16x16x32_bf16 v[150:153], v[86:89], v[166:169], v[150:153]
	v_mfma_f32_16x16x32_bf16 v[146:149], v[98:101], v[166:169], v[146:149]
	v_mfma_f32_16x16x32_bf16 v[134:137], v[86:89], v[174:177], v[134:137]
	v_mfma_f32_16x16x32_bf16 v[130:133], v[98:101], v[174:177], v[130:133]
	v_mfma_f32_16x16x32_bf16 v[118:121], v[86:89], v[182:185], v[118:121]
	v_mfma_f32_16x16x32_bf16 v[114:117], v[98:101], v[182:185], v[114:117]
	v_mfma_f32_16x16x32_bf16 v[102:105], v[86:89], v[190:193], v[102:105]
	v_mfma_f32_16x16x32_bf16 v[90:93], v[98:101], v[190:193], v[90:93]
	s_setprio 0
	s_barrier
	s_add_i32 s34, s57, s46
	v_lshl_add_u64 v[200:201], s[38:39], 0, v[210:211]
	s_mov_b32 m0, s34
	ds_read_b128 v[162:165], v235 offset:16384
	ds_read_b128 v[166:169], v235 offset:17408
	ds_read_b128 v[170:173], v235 offset:18432
	ds_read_b128 v[174:177], v235 offset:19456
	ds_read_b128 v[178:181], v235 offset:20480
	ds_read_b128 v[182:185], v235 offset:21504
	ds_read_b128 v[186:189], v235 offset:22528
	ds_read_b128 v[190:193], v235 offset:23552
	global_load_lds_dwordx4 v[200:201], off
	s_add_i32 m0, s34, 0x2000
	s_add_u32 s34, s38, 0x200000
	v_lshl_add_u64 v[202:203], s[38:39], 0, v[194:195]
	s_addc_u32 s35, s39, 0
	s_add_i32 s57, s58, s46
	global_load_lds_dwordx4 v[202:203], off
	s_mov_b32 m0, s57
	v_lshl_add_u64 v[206:207], s[40:41], 0, v[194:195]
	global_load_lds_dwordx4 v210, s[34:35]
	s_add_i32 m0, s57, 0x2000
	s_nop 0
	global_load_lds_dwordx4 v194, s[34:35]
	v_lshl_add_u64 v[204:205], s[40:41], 0, v[210:211]
	s_mov_b32 m0, s47
	s_nop 0
	global_load_lds_dwordx4 v[204:205], off
	s_mov_b32 m0, s48
	s_nop 0
	global_load_lds_dwordx4 v[206:207], off
	s_waitcnt vmcnt(8) lgkmcnt(0)
	s_barrier
	s_setprio 1
	v_mfma_f32_16x16x32_bf16 v[62:65], v[66:69], v[162:165], v[62:65]
	v_mfma_f32_16x16x32_bf16 v[58:61], v[74:77], v[162:165], v[58:61]
	v_mfma_f32_16x16x32_bf16 v[46:49], v[66:69], v[170:173], v[46:49]
	v_mfma_f32_16x16x32_bf16 v[42:45], v[74:77], v[170:173], v[42:45]
	v_mfma_f32_16x16x32_bf16 v[30:33], v[66:69], v[178:181], v[30:33]
	v_mfma_f32_16x16x32_bf16 v[26:29], v[74:77], v[178:181], v[26:29]
	v_mfma_f32_16x16x32_bf16 v[14:17], v[66:69], v[186:189], v[14:17]
	v_mfma_f32_16x16x32_bf16 v[10:13], v[74:77], v[186:189], v[10:13]
	v_mfma_f32_16x16x32_bf16 v[62:65], v[70:73], v[166:169], v[62:65]
	v_mfma_f32_16x16x32_bf16 v[58:61], v[78:81], v[166:169], v[58:61]
	v_mfma_f32_16x16x32_bf16 v[46:49], v[70:73], v[174:177], v[46:49]
	v_mfma_f32_16x16x32_bf16 v[42:45], v[78:81], v[174:177], v[42:45]
	v_mfma_f32_16x16x32_bf16 v[30:33], v[70:73], v[182:185], v[30:33]
	v_mfma_f32_16x16x32_bf16 v[26:29], v[78:81], v[182:185], v[26:29]
	v_mfma_f32_16x16x32_bf16 v[14:17], v[70:73], v[190:193], v[14:17]
	v_mfma_f32_16x16x32_bf16 v[10:13], v[78:81], v[190:193], v[10:13]
	v_mfma_f32_16x16x32_bf16 v[54:57], v[82:85], v[162:165], v[54:57]
	v_mfma_f32_16x16x32_bf16 v[50:53], v[94:97], v[162:165], v[50:53]
	v_mfma_f32_16x16x32_bf16 v[38:41], v[82:85], v[170:173], v[38:41]
	v_mfma_f32_16x16x32_bf16 v[34:37], v[94:97], v[170:173], v[34:37]
	v_mfma_f32_16x16x32_bf16 v[22:25], v[82:85], v[178:181], v[22:25]
	v_mfma_f32_16x16x32_bf16 v[18:21], v[94:97], v[178:181], v[18:21]
	v_mfma_f32_16x16x32_bf16 v[6:9], v[82:85], v[186:189], v[6:9]
	v_mfma_f32_16x16x32_bf16 v[2:5], v[94:97], v[186:189], v[2:5]
	v_mfma_f32_16x16x32_bf16 v[54:57], v[86:89], v[166:169], v[54:57]
	v_mfma_f32_16x16x32_bf16 v[50:53], v[98:101], v[166:169], v[50:53]
	v_mfma_f32_16x16x32_bf16 v[38:41], v[86:89], v[174:177], v[38:41]
	v_mfma_f32_16x16x32_bf16 v[34:37], v[98:101], v[174:177], v[34:37]
	v_mfma_f32_16x16x32_bf16 v[22:25], v[86:89], v[182:185], v[22:25]
	v_mfma_f32_16x16x32_bf16 v[18:21], v[98:101], v[182:185], v[18:21]
	v_mfma_f32_16x16x32_bf16 v[6:9], v[86:89], v[190:193], v[6:9]
	v_mfma_f32_16x16x32_bf16 v[2:5], v[98:101], v[190:193], v[2:5]
	s_setprio 0
	s_barrier
	s_add_i32 s57, 0, 0x18000
	s_add_i32 s58, 0, 0x1c000
	v_add_u32_e32 v78, s57, v233
	v_add_u32_e32 v98, s58, v233
	ds_read_b128 v[66:69], v78
	ds_read_b128 v[70:73], v78 offset:1024
	ds_read_b128 v[74:77], v78 offset:2048
	ds_read_b128 v[78:81], v78 offset:3072
	ds_read_b128 v[82:85], v98
	ds_read_b128 v[86:89], v98 offset:1024
	ds_read_b128 v[94:97], v98 offset:2048
	ds_read_b128 v[98:101], v98 offset:3072
	s_add_u32 s34, s40, 0x200000
	s_addc_u32 s35, s41, 0
	s_mov_b32 m0, s49
	ds_read_b128 v[162:165], v235 offset:32768
	ds_read_b128 v[166:169], v235 offset:33792
	ds_read_b128 v[170:173], v235 offset:34816
	ds_read_b128 v[174:177], v235 offset:35840
	ds_read_b128 v[178:181], v235 offset:36864
	ds_read_b128 v[182:185], v235 offset:37888
	ds_read_b128 v[186:189], v235 offset:38912
	ds_read_b128 v[190:193], v235 offset:39936
	global_load_lds_dwordx4 v210, s[34:35]
	s_mov_b32 m0, s50
	s_nop 0
	global_load_lds_dwordx4 v194, s[34:35]
	s_waitcnt vmcnt(8) lgkmcnt(0)
	s_barrier
	s_setprio 1
	v_mfma_f32_16x16x32_bf16 v[158:161], v[66:69], v[162:165], v[158:161]
	v_mfma_f32_16x16x32_bf16 v[154:157], v[74:77], v[162:165], v[154:157]
	v_mfma_f32_16x16x32_bf16 v[142:145], v[66:69], v[170:173], v[142:145]
	v_mfma_f32_16x16x32_bf16 v[138:141], v[74:77], v[170:173], v[138:141]
	v_mfma_f32_16x16x32_bf16 v[126:129], v[66:69], v[178:181], v[126:129]
	v_mfma_f32_16x16x32_bf16 v[122:125], v[74:77], v[178:181], v[122:125]
	v_mfma_f32_16x16x32_bf16 v[110:113], v[66:69], v[186:189], v[110:113]
	v_mfma_f32_16x16x32_bf16 v[106:109], v[74:77], v[186:189], v[106:109]
	v_mfma_f32_16x16x32_bf16 v[158:161], v[70:73], v[166:169], v[158:161]
	v_mfma_f32_16x16x32_bf16 v[154:157], v[78:81], v[166:169], v[154:157]
	v_mfma_f32_16x16x32_bf16 v[142:145], v[70:73], v[174:177], v[142:145]
	v_mfma_f32_16x16x32_bf16 v[138:141], v[78:81], v[174:177], v[138:141]
	v_mfma_f32_16x16x32_bf16 v[126:129], v[70:73], v[182:185], v[126:129]
	v_mfma_f32_16x16x32_bf16 v[122:125], v[78:81], v[182:185], v[122:125]
	v_mfma_f32_16x16x32_bf16 v[110:113], v[70:73], v[190:193], v[110:113]
	v_mfma_f32_16x16x32_bf16 v[106:109], v[78:81], v[190:193], v[106:109]
	v_mfma_f32_16x16x32_bf16 v[150:153], v[82:85], v[162:165], v[150:153]
	v_mfma_f32_16x16x32_bf16 v[146:149], v[94:97], v[162:165], v[146:149]
	v_mfma_f32_16x16x32_bf16 v[134:137], v[82:85], v[170:173], v[134:137]
	v_mfma_f32_16x16x32_bf16 v[130:133], v[94:97], v[170:173], v[130:133]
	v_mfma_f32_16x16x32_bf16 v[118:121], v[82:85], v[178:181], v[118:121]
	v_mfma_f32_16x16x32_bf16 v[114:117], v[94:97], v[178:181], v[114:117]
	v_mfma_f32_16x16x32_bf16 v[102:105], v[82:85], v[186:189], v[102:105]
	v_mfma_f32_16x16x32_bf16 v[90:93], v[94:97], v[186:189], v[90:93]
	v_mfma_f32_16x16x32_bf16 v[150:153], v[86:89], v[166:169], v[150:153]
	v_mfma_f32_16x16x32_bf16 v[146:149], v[98:101], v[166:169], v[146:149]
	v_mfma_f32_16x16x32_bf16 v[134:137], v[86:89], v[174:177], v[134:137]
	v_mfma_f32_16x16x32_bf16 v[130:133], v[98:101], v[174:177], v[130:133]
	v_mfma_f32_16x16x32_bf16 v[118:121], v[86:89], v[182:185], v[118:121]
	v_mfma_f32_16x16x32_bf16 v[114:117], v[98:101], v[182:185], v[114:117]
	v_mfma_f32_16x16x32_bf16 v[102:105], v[86:89], v[190:193], v[102:105]
	v_mfma_f32_16x16x32_bf16 v[90:93], v[98:101], v[190:193], v[90:93]
	s_setprio 0
	s_barrier
	s_add_i32 s34, s57, s46
	v_lshl_add_u64 v[200:201], v[200:201], 0, s[64:65]
	s_mov_b32 m0, s34
	ds_read_b128 v[162:165], v235 offset:49152
	ds_read_b128 v[166:169], v235 offset:50176
	ds_read_b128 v[170:173], v235 offset:51200
	ds_read_b128 v[174:177], v235 offset:52224
	ds_read_b128 v[178:181], v235 offset:53248
	ds_read_b128 v[182:185], v235 offset:54272
	ds_read_b128 v[186:189], v235 offset:55296
	ds_read_b128 v[190:193], v235 offset:56320
	global_load_lds_dwordx4 v[200:201], off
	s_add_i32 m0, s34, 0x2000
	s_add_u32 s34, s38, 0x200080
	v_lshl_add_u64 v[200:201], v[202:203], 0, s[64:65]
	s_addc_u32 s35, s39, 0
	s_add_i32 s38, s58, s46
	global_load_lds_dwordx4 v[200:201], off
	s_mov_b32 m0, s38
	s_nop 0
	global_load_lds_dwordx4 v210, s[34:35]
	s_add_i32 m0, s38, 0x2000
	s_nop 0
	global_load_lds_dwordx4 v194, s[34:35]
	v_lshl_add_u64 v[200:201], v[204:205], 0, s[64:65]
	s_mov_b32 m0, s51
	s_nop 0
	global_load_lds_dwordx4 v[200:201], off
	v_lshl_add_u64 v[200:201], v[206:207], 0, s[64:65]
	s_mov_b32 m0, s52
	s_nop 0
	global_load_lds_dwordx4 v[200:201], off
	s_waitcnt vmcnt(8) lgkmcnt(0)
	s_barrier
	s_setprio 1
	v_mfma_f32_16x16x32_bf16 v[62:65], v[66:69], v[162:165], v[62:65]
	v_mfma_f32_16x16x32_bf16 v[58:61], v[74:77], v[162:165], v[58:61]
	v_mfma_f32_16x16x32_bf16 v[46:49], v[66:69], v[170:173], v[46:49]
	v_mfma_f32_16x16x32_bf16 v[42:45], v[74:77], v[170:173], v[42:45]
	v_mfma_f32_16x16x32_bf16 v[30:33], v[66:69], v[178:181], v[30:33]
	v_mfma_f32_16x16x32_bf16 v[26:29], v[74:77], v[178:181], v[26:29]
	v_mfma_f32_16x16x32_bf16 v[14:17], v[66:69], v[186:189], v[14:17]
	v_mfma_f32_16x16x32_bf16 v[10:13], v[74:77], v[186:189], v[10:13]
	v_mfma_f32_16x16x32_bf16 v[62:65], v[70:73], v[166:169], v[62:65]
	v_mfma_f32_16x16x32_bf16 v[58:61], v[78:81], v[166:169], v[58:61]
	v_mfma_f32_16x16x32_bf16 v[46:49], v[70:73], v[174:177], v[46:49]
	v_mfma_f32_16x16x32_bf16 v[42:45], v[78:81], v[174:177], v[42:45]
	v_mfma_f32_16x16x32_bf16 v[30:33], v[70:73], v[182:185], v[30:33]
	v_mfma_f32_16x16x32_bf16 v[26:29], v[78:81], v[182:185], v[26:29]
	v_mfma_f32_16x16x32_bf16 v[14:17], v[70:73], v[190:193], v[14:17]
	v_mfma_f32_16x16x32_bf16 v[10:13], v[78:81], v[190:193], v[10:13]
	v_mfma_f32_16x16x32_bf16 v[54:57], v[82:85], v[162:165], v[54:57]
	v_mfma_f32_16x16x32_bf16 v[50:53], v[94:97], v[162:165], v[50:53]
	v_mfma_f32_16x16x32_bf16 v[38:41], v[82:85], v[170:173], v[38:41]
	v_mfma_f32_16x16x32_bf16 v[34:37], v[94:97], v[170:173], v[34:37]
	v_mfma_f32_16x16x32_bf16 v[22:25], v[82:85], v[178:181], v[22:25]
	v_mfma_f32_16x16x32_bf16 v[18:21], v[94:97], v[178:181], v[18:21]
	v_mfma_f32_16x16x32_bf16 v[6:9], v[82:85], v[186:189], v[6:9]
	v_mfma_f32_16x16x32_bf16 v[2:5], v[94:97], v[186:189], v[2:5]
	v_mfma_f32_16x16x32_bf16 v[54:57], v[86:89], v[166:169], v[54:57]
	v_mfma_f32_16x16x32_bf16 v[50:53], v[98:101], v[166:169], v[50:53]
	v_mfma_f32_16x16x32_bf16 v[38:41], v[86:89], v[174:177], v[38:41]
	v_mfma_f32_16x16x32_bf16 v[34:37], v[98:101], v[174:177], v[34:37]
	v_mfma_f32_16x16x32_bf16 v[22:25], v[86:89], v[182:185], v[22:25]
	v_mfma_f32_16x16x32_bf16 v[18:21], v[98:101], v[182:185], v[18:21]
	v_mfma_f32_16x16x32_bf16 v[6:9], v[86:89], v[190:193], v[6:9]
	v_mfma_f32_16x16x32_bf16 v[2:5], v[98:101], v[190:193], v[2:5]
	s_setprio 0
	s_barrier
	s_add_i32 s56, s56, 2
	s_add_u32 s54, s54, 0x100
	s_addc_u32 s55, s55, 0
	s_cmpk_gt_u32 s56, 0x7d
	s_mov_b64 s[34:35], s[36:37]
	s_cbranch_scc0 .LBB0_1180
	s_and_b64 vcc, exec, s[20:21]
	s_cbranch_vccz .LBB0_1183
	s_barrier
